# GEMM K-loops: vmcnt(0)+barrier moved later in the K-tile; q_tile GEMM iterations re-rolled into a loop (code size)
# speedup vs baseline: 1.0735x; 1.0201x over previous
.LBB0_90:
	ds_read_b128 v[128:131], v148 offset:32768
	ds_read_b128 v[168:171], v149
	ds_read_b128 v[156:159], v148 offset:34816
	ds_read_b128 v[160:163], v148 offset:36864
	ds_read_b128 v[164:167], v148 offset:38912
	ds_read_b128 v[172:175], v149 offset:2048
	ds_read_b128 v[176:179], v149 offset:4096
	ds_read_b128 v[180:183], v149 offset:6144
	ds_read_b128 v[184:187], v149 offset:8192
	ds_read_b128 v[188:191], v149 offset:10240
	ds_read_b128 v[192:195], v149 offset:12288
	ds_read_b128 v[196:199], v149 offset:14336
	s_waitcnt lgkmcnt(10)
	v_mfma_f32_16x16x32_bf16 v[112:115], v[128:131], v[168:171], v[112:115]
	s_mov_b64 s[8:9], 0x19dc5080
	s_mov_b32 m0, s88
	s_add_i32 s18, s6, 1
	s_waitcnt lgkmcnt(9)
	v_mfma_f32_16x16x32_bf16 v[124:127], v[156:159], v[168:171], v[124:127]
	s_add_i32 s7, s6, 2
	s_cmp_lt_u32 s6, 30
	s_waitcnt lgkmcnt(8)
	v_mfma_f32_16x16x32_bf16 v[120:123], v[160:163], v[168:171], v[120:123]
	s_waitcnt lgkmcnt(7)
	v_mfma_f32_16x16x32_bf16 v[116:119], v[164:167], v[168:171], v[116:119]
	v_lshl_add_u64 v[168:169], v[138:139], 0, v[132:133]
	v_lshl_add_u64 v[170:171], v[168:169], 0, s[8:9]
	s_mov_b64 s[8:9], 0x19e07080
	global_load_lds_dwordx4 v[170:171], off
	v_lshl_add_u64 v[170:171], v[168:169], 0, s[8:9]
	s_mov_b32 m0, s92
	s_mov_b64 s[8:9], 0x19e49080
	s_waitcnt lgkmcnt(6)
	v_mfma_f32_16x16x32_bf16 v[96:99], v[128:131], v[172:175], v[96:99]
	v_lshl_add_u64 v[138:139], v[138:139], 0, s[34:35]
	v_mfma_f32_16x16x32_bf16 v[108:111], v[156:159], v[172:175], v[108:111]
	v_mfma_f32_16x16x32_bf16 v[104:107], v[160:163], v[172:175], v[104:107]
	v_mfma_f32_16x16x32_bf16 v[100:103], v[164:167], v[172:175], v[100:103]
	global_load_lds_dwordx4 v[170:171], off
	v_lshl_add_u64 v[170:171], v[168:169], 0, s[8:9]
	s_mov_b32 m0, s93
	s_mov_b64 s[8:9], 0x19e8b080
	s_waitcnt lgkmcnt(5)
	v_mfma_f32_16x16x32_bf16 v[80:83], v[128:131], v[176:179], v[80:83]
	v_lshl_add_u64 v[168:169], v[168:169], 0, s[8:9]
	s_mov_b64 s[8:9], 0x245080
	v_mfma_f32_16x16x32_bf16 v[92:95], v[156:159], v[176:179], v[92:95]
	v_mfma_f32_16x16x32_bf16 v[88:91], v[160:163], v[176:179], v[88:91]
	v_mfma_f32_16x16x32_bf16 v[84:87], v[164:167], v[176:179], v[84:87]
	global_load_lds_dwordx4 v[170:171], off
	s_mov_b32 m0, s94
	s_waitcnt lgkmcnt(4)
	v_mfma_f32_16x16x32_bf16 v[64:67], v[128:131], v[180:183], v[64:67]
	v_mfma_f32_16x16x32_bf16 v[76:79], v[156:159], v[180:183], v[76:79]
	v_mfma_f32_16x16x32_bf16 v[72:75], v[160:163], v[180:183], v[72:75]
	v_mfma_f32_16x16x32_bf16 v[68:71], v[164:167], v[180:183], v[68:71]
	global_load_lds_dwordx4 v[168:169], off
	s_mov_b32 m0, s89
	s_waitcnt lgkmcnt(3)
	v_mfma_f32_16x16x32_bf16 v[48:51], v[128:131], v[184:187], v[48:51]
	v_mfma_f32_16x16x32_bf16 v[60:63], v[156:159], v[184:187], v[60:63]
	v_mfma_f32_16x16x32_bf16 v[56:59], v[160:163], v[184:187], v[56:59]
	v_mfma_f32_16x16x32_bf16 v[52:55], v[164:167], v[184:187], v[52:55]
	s_waitcnt lgkmcnt(2)
	v_mfma_f32_16x16x32_bf16 v[32:35], v[128:131], v[188:191], v[32:35]
	v_mfma_f32_16x16x32_bf16 v[44:47], v[156:159], v[188:191], v[44:47]
	v_mfma_f32_16x16x32_bf16 v[40:43], v[160:163], v[188:191], v[40:43]
	v_mfma_f32_16x16x32_bf16 v[36:39], v[164:167], v[188:191], v[36:39]
	s_waitcnt lgkmcnt(1)
	v_mfma_f32_16x16x32_bf16 v[12:15], v[128:131], v[192:195], v[12:15]
	v_mfma_f32_16x16x32_bf16 v[24:27], v[156:159], v[192:195], v[24:27]
	v_mfma_f32_16x16x32_bf16 v[20:23], v[160:163], v[192:195], v[20:23]
	v_mfma_f32_16x16x32_bf16 v[16:19], v[164:167], v[192:195], v[16:19]
	s_waitcnt lgkmcnt(0)
	v_mfma_f32_16x16x32_bf16 v[0:3], v[128:131], v[196:199], v[0:3]
	v_mfma_f32_16x16x32_bf16 v[8:11], v[156:159], v[196:199], v[8:11]
	v_mfma_f32_16x16x32_bf16 v[4:7], v[160:163], v[196:199], v[4:7]
	v_mfma_f32_16x16x32_bf16 v[28:31], v[164:167], v[196:199], v[28:31]
	ds_read_b128 v[128:131], v150 offset:32768
	ds_read_b128 v[168:171], v151
	ds_read_b128 v[156:159], v150 offset:34816
	ds_read_b128 v[160:163], v150 offset:36864
	ds_read_b128 v[164:167], v150 offset:38912
	ds_read_b128 v[172:175], v151 offset:2048
	ds_read_b128 v[176:179], v151 offset:4096
	ds_read_b128 v[180:183], v151 offset:6144
	ds_read_b128 v[184:187], v151 offset:8192
	ds_read_b128 v[188:191], v151 offset:10240
	ds_read_b128 v[192:195], v151 offset:12288
	ds_read_b128 v[196:199], v151 offset:14336
	s_waitcnt lgkmcnt(10)
	v_mfma_f32_16x16x32_bf16 v[112:115], v[128:131], v[168:171], v[112:115]
	s_waitcnt lgkmcnt(9)
	v_mfma_f32_16x16x32_bf16 v[124:127], v[156:159], v[168:171], v[124:127]
	s_waitcnt lgkmcnt(8)
	v_mfma_f32_16x16x32_bf16 v[120:123], v[160:163], v[168:171], v[120:123]
	s_waitcnt lgkmcnt(7)
	v_mfma_f32_16x16x32_bf16 v[116:119], v[164:167], v[168:171], v[116:119]
	v_lshl_add_u64 v[168:169], v[140:141], 0, v[132:133]
	v_lshl_add_u64 v[170:171], v[168:169], 0, s[8:9]
	s_mov_b64 s[8:9], 0x287080
	global_load_lds_dwordx4 v[170:171], off
	v_lshl_add_u64 v[170:171], v[168:169], 0, s[8:9]
	s_mov_b32 m0, s95
	s_waitcnt lgkmcnt(6)
	v_mfma_f32_16x16x32_bf16 v[96:99], v[128:131], v[172:175], v[96:99]
	s_cselect_b64 s[8:9], -1, 0
	s_and_b64 vcc, s[8:9], exec
	s_cselect_b32 s6, s7, s18
	v_mfma_f32_16x16x32_bf16 v[108:111], v[156:159], v[172:175], v[108:111]
	s_lshl_b32 s18, s6, 7
	v_lshl_add_u64 v[140:141], v[140:141], 0, s[34:35]
	s_mov_b32 s6, s7
	v_mfma_f32_16x16x32_bf16 v[104:107], v[160:163], v[172:175], v[104:107]
	v_mfma_f32_16x16x32_bf16 v[100:103], v[164:167], v[172:175], v[100:103]
	global_load_lds_dwordx4 v[170:171], off
	v_lshl_add_u64 v[170:171], v[168:169], 0, s[28:29]
	s_mov_b32 m0, s96
	s_waitcnt lgkmcnt(5)
; #define G3_LDA(buf, kt, i) __builtin_amdgcn_global_load_lds((const unsigned*)(ga + (size_t)((i) * 64) * lda + (kt) * 64), (lds_u32*)(sdst + (buf) * STAGE + (i) * 8192), 16, 0, 0)
; #define G3_LDB(buf, kt, i) __builtin_amdgcn_global_load_lds((const unsigned*)(gb + (size_t)((i) * 64) * ldb + (kt) * 64), (lds_u32*)(sdst + (buf) * STAGE + B_OFF + (i) * 8192), 16, 0, 0)
; DI void gemm3_mainloop(const int wave8, const int lane, const bf16_t* __restrict__ A, int lda, const bf16_t* __restrict__ Bt, int ldb, int K,
;                        unsigned char* smem, f32x4 (&acc)[8][4]) {
;     ...
;     asm volatile("s_waitcnt vmcnt(0)" ::: "memory");
;     G3_LDA(0, 0, 0); G3_LDA(0, 0, 1); G3_LDA(0, 0, 2); G3_LDA(0, 0, 3); G3_LDB(0, 0, 0); G3_LDB(0, 0, 1); G3_LDB(0, 0, 2); G3_LDB(0, 0, 3);
;     asm volatile("s_waitcnt vmcnt(0)" ::: "memory");
;     __builtin_amdgcn_s_barrier();
;     for (int kt = 0; kt < nk; kt += 2) { G3_STEP(0, 1, kt); G3_STEP(1, 0, kt + 1); }
	v_mfma_f32_16x16x32_bf16 v[80:83], v[128:131], v[176:179], v[80:83]
	v_lshl_add_u64 v[168:169], v[168:169], 0, s[30:31]
	v_mfma_f32_16x16x32_bf16 v[92:95], v[156:159], v[176:179], v[92:95]
	v_mfma_f32_16x16x32_bf16 v[88:91], v[160:163], v[176:179], v[88:91]
	v_mfma_f32_16x16x32_bf16 v[84:87], v[164:167], v[176:179], v[84:87]
	global_load_lds_dwordx4 v[170:171], off
	s_mov_b32 m0, s97
	s_waitcnt lgkmcnt(4)
	v_mfma_f32_16x16x32_bf16 v[64:67], v[128:131], v[180:183], v[64:67]
	v_mfma_f32_16x16x32_bf16 v[76:79], v[156:159], v[180:183], v[76:79]
	v_mfma_f32_16x16x32_bf16 v[72:75], v[160:163], v[180:183], v[72:75]
	v_mfma_f32_16x16x32_bf16 v[68:71], v[164:167], v[180:183], v[68:71]
	global_load_lds_dwordx4 v[168:169], off
	s_waitcnt lgkmcnt(3)
	v_mfma_f32_16x16x32_bf16 v[48:51], v[128:131], v[184:187], v[48:51]
	s_mov_b32 m0, s0
	v_mfma_f32_16x16x32_bf16 v[60:63], v[156:159], v[184:187], v[60:63]
	v_mfma_f32_16x16x32_bf16 v[56:59], v[160:163], v[184:187], v[56:59]
	v_mfma_f32_16x16x32_bf16 v[52:55], v[164:167], v[184:187], v[52:55]
	s_waitcnt lgkmcnt(2)
	v_mfma_f32_16x16x32_bf16 v[32:35], v[128:131], v[188:191], v[32:35]
	v_mfma_f32_16x16x32_bf16 v[44:47], v[156:159], v[188:191], v[44:47]
	v_mfma_f32_16x16x32_bf16 v[40:43], v[160:163], v[188:191], v[40:43]
	v_mfma_f32_16x16x32_bf16 v[36:39], v[164:167], v[188:191], v[36:39]
	s_waitcnt lgkmcnt(1)
	v_mfma_f32_16x16x32_bf16 v[12:15], v[128:131], v[192:195], v[12:15]
	v_mfma_f32_16x16x32_bf16 v[24:27], v[156:159], v[192:195], v[24:27]
	v_mfma_f32_16x16x32_bf16 v[20:23], v[160:163], v[192:195], v[20:23]
	v_mfma_f32_16x16x32_bf16 v[16:19], v[164:167], v[192:195], v[16:19]
	s_waitcnt vmcnt(0)
	s_barrier
	s_waitcnt lgkmcnt(0)
	v_mfma_f32_16x16x32_bf16 v[0:3], v[128:131], v[196:199], v[0:3]
	v_mfma_f32_16x16x32_bf16 v[8:11], v[156:159], v[196:199], v[8:11]
	v_mfma_f32_16x16x32_bf16 v[4:7], v[160:163], v[196:199], v[4:7]
	v_mfma_f32_16x16x32_bf16 v[28:31], v[164:167], v[196:199], v[28:31]
	ds_read_b128 v[128:131], v152
	ds_read_b128 v[168:171], v153
	ds_read_b128 v[156:159], v152 offset:2048
	ds_read_b128 v[160:163], v152 offset:4096
	ds_read_b128 v[164:167], v152 offset:6144
	ds_read_b128 v[172:175], v153 offset:2048
	ds_read_b128 v[176:179], v153 offset:4096
	ds_read_b128 v[180:183], v153 offset:6144
	ds_read_b128 v[184:187], v153 offset:8192
	ds_read_b128 v[188:191], v153 offset:10240
	ds_read_b128 v[192:195], v153 offset:12288
	ds_read_b128 v[196:199], v153 offset:14336
	s_waitcnt lgkmcnt(10)
	v_mfma_f32_16x16x32_bf16 v[112:115], v[128:131], v[168:171], v[112:115]
	s_waitcnt lgkmcnt(9)
	v_mfma_f32_16x16x32_bf16 v[124:127], v[156:159], v[168:171], v[124:127]
	s_waitcnt lgkmcnt(8)
	v_mfma_f32_16x16x32_bf16 v[120:123], v[160:163], v[168:171], v[120:123]
	s_waitcnt lgkmcnt(7)
	v_mfma_f32_16x16x32_bf16 v[116:119], v[164:167], v[168:171], v[116:119]
	v_lshl_add_u64 v[168:169], v[134:135], 0, s[18:19]
	global_load_lds_dwordx4 v[168:169], off
	v_lshl_add_u64 v[170:171], v[168:169], 0, s[22:23]
	s_mov_b32 m0, s55
	s_waitcnt lgkmcnt(6)
	v_mfma_f32_16x16x32_bf16 v[96:99], v[128:131], v[172:175], v[96:99]
	v_mfma_f32_16x16x32_bf16 v[108:111], v[156:159], v[172:175], v[108:111]
	v_mfma_f32_16x16x32_bf16 v[104:107], v[160:163], v[172:175], v[104:107]
	v_mfma_f32_16x16x32_bf16 v[100:103], v[164:167], v[172:175], v[100:103]
	global_load_lds_dwordx4 v[170:171], off
	v_lshl_add_u64 v[170:171], v[168:169], 0, s[24:25]
	s_mov_b32 m0, s87
	s_waitcnt lgkmcnt(5)
	v_mfma_f32_16x16x32_bf16 v[80:83], v[128:131], v[176:179], v[80:83]
	v_lshl_add_u64 v[168:169], v[168:169], 0, s[26:27]
	v_mfma_f32_16x16x32_bf16 v[92:95], v[156:159], v[176:179], v[92:95]
	v_mfma_f32_16x16x32_bf16 v[88:91], v[160:163], v[176:179], v[88:91]
	v_mfma_f32_16x16x32_bf16 v[84:87], v[164:167], v[176:179], v[84:87]
	global_load_lds_dwordx4 v[170:171], off
	s_mov_b32 m0, s69
	s_waitcnt lgkmcnt(4)
	v_mfma_f32_16x16x32_bf16 v[64:67], v[128:131], v[180:183], v[64:67]
	v_mfma_f32_16x16x32_bf16 v[76:79], v[156:159], v[180:183], v[76:79]
	v_mfma_f32_16x16x32_bf16 v[72:75], v[160:163], v[180:183], v[72:75]
	v_mfma_f32_16x16x32_bf16 v[68:71], v[164:167], v[180:183], v[68:71]
	global_load_lds_dwordx4 v[168:169], off
	s_mov_b32 m0, s68
	s_waitcnt lgkmcnt(3)
	v_mfma_f32_16x16x32_bf16 v[48:51], v[128:131], v[184:187], v[48:51]
	v_mfma_f32_16x16x32_bf16 v[60:63], v[156:159], v[184:187], v[60:63]
	v_mfma_f32_16x16x32_bf16 v[56:59], v[160:163], v[184:187], v[56:59]
	v_mfma_f32_16x16x32_bf16 v[52:55], v[164:167], v[184:187], v[52:55]
	s_waitcnt lgkmcnt(2)
	v_mfma_f32_16x16x32_bf16 v[32:35], v[128:131], v[188:191], v[32:35]
	v_mfma_f32_16x16x32_bf16 v[44:47], v[156:159], v[188:191], v[44:47]
	v_mfma_f32_16x16x32_bf16 v[40:43], v[160:163], v[188:191], v[40:43]
	v_mfma_f32_16x16x32_bf16 v[36:39], v[164:167], v[188:191], v[36:39]
	s_waitcnt lgkmcnt(1)
	v_mfma_f32_16x16x32_bf16 v[12:15], v[128:131], v[192:195], v[12:15]
	v_mfma_f32_16x16x32_bf16 v[24:27], v[156:159], v[192:195], v[24:27]
	v_mfma_f32_16x16x32_bf16 v[20:23], v[160:163], v[192:195], v[20:23]
	v_mfma_f32_16x16x32_bf16 v[16:19], v[164:167], v[192:195], v[16:19]
	s_waitcnt lgkmcnt(0)
	v_mfma_f32_16x16x32_bf16 v[0:3], v[128:131], v[196:199], v[0:3]
	v_mfma_f32_16x16x32_bf16 v[8:11], v[156:159], v[196:199], v[8:11]
	v_mfma_f32_16x16x32_bf16 v[4:7], v[160:163], v[196:199], v[4:7]
	v_mfma_f32_16x16x32_bf16 v[28:31], v[164:167], v[196:199], v[28:31]
	ds_read_b128 v[156:159], v154
	ds_read_b128 v[168:171], v155
	ds_read_b128 v[160:163], v154 offset:2048
	ds_read_b128 v[164:167], v154 offset:4096
	ds_read_b128 v[128:131], v154 offset:6144
	ds_read_b128 v[172:175], v155 offset:2048
	ds_read_b128 v[176:179], v155 offset:4096
	ds_read_b128 v[180:183], v155 offset:6144
	ds_read_b128 v[184:187], v155 offset:8192
	ds_read_b128 v[188:191], v155 offset:10240
	ds_read_b128 v[192:195], v155 offset:12288
	ds_read_b128 v[196:199], v155 offset:14336
	s_waitcnt lgkmcnt(10)
; DI unsigned pk2(float a, float b) { f2_t v = {a, b}; bf2_t r = __builtin_convertvector(v, bf2_t); return __builtin_bit_cast(unsigned, r); }
; #define G3_LDA(buf, kt, i) __builtin_amdgcn_global_load_lds((const unsigned*)(ga + (size_t)((i) * 64) * lda + (kt) * 64), (lds_u32*)(sdst + (buf) * STAGE + (i) * 8192), 16, 0, 0)
; #define G3_LDB(buf, kt, i) __builtin_amdgcn_global_load_lds((const unsigned*)(gb + (size_t)((i) * 64) * ldb + (kt) * 64), (lds_u32*)(sdst + (buf) * STAGE + B_OFF + (i) * 8192), 16, 0, 0)
; DI void gemm3_mainloop(const int wave8, const int lane, const bf16_t* __restrict__ A, int lda, const bf16_t* __restrict__ Bt, int ldb, int K,
;                        unsigned char* smem, f32x4 (&acc)[8][4]) {
;     ...
;     asm volatile("s_waitcnt vmcnt(0)" ::: "memory");
;     G3_LDA(0, 0, 0); G3_LDA(0, 0, 1); G3_LDA(0, 0, 2); G3_LDA(0, 0, 3); G3_LDB(0, 0, 0); G3_LDB(0, 0, 1); G3_LDB(0, 0, 2); G3_LDB(0, 0, 3);
;     asm volatile("s_waitcnt vmcnt(0)" ::: "memory");
;     __builtin_amdgcn_s_barrier();
;     for (int kt = 0; kt < nk; kt += 2) { G3_STEP(0, 1, kt); G3_STEP(1, 0, kt + 1); }
; DI void phase1(const Params& p, unsigned char* smem) {
;     ...
;         const int c128 = nt * 2 + (wn >> 1);
;         if (c128 >= 47) return;
;         bf16_t* dst; int ld, c0;
;         if (c128 < 23) { dst = pa; ld = LDPA; c0 = c128 * 128; } else { dst = pb; ld = LDPB; c0 = (c128 - 23) * 128; }
; #pragma unroll
;         for (int i = 0; i < 8; ++i) {
;             const int m = mt * 256 + wm * 128 + i * 16 + fr;
;             float ss = 0.f;
; #pragma unroll
;             for (int j = 0; j < 4; ++j) {
;                 const f32x4 v = acc[i][j];
;                 ss += v.x * v.x + v.y * v.y + v.z * v.z + v.w * v.w;
;                 u32x2 o; o.x = pk2(v.x, v.y); o.y = pk2(v.z, v.w);
;                 *(u32x2*)(dst + (size_t)m * ld + c0 + (wn & 1) * 64 + j * 16 + fq * 4) = o;
;             }
;             if (c128 < 6) {
;                 ss += __shfl_xor(ss, 16); ss += __shfl_xor(ss, 32);
;                 if (fq == 0) atomicAdd(ssq + (c128 < 4 ? 0 : T_) + m, ss);
	v_mfma_f32_16x16x32_bf16 v[112:115], v[156:159], v[168:171], v[112:115]
	s_waitcnt lgkmcnt(9)
	v_mfma_f32_16x16x32_bf16 v[124:127], v[160:163], v[168:171], v[124:127]
	s_waitcnt lgkmcnt(8)
	v_mfma_f32_16x16x32_bf16 v[120:123], v[164:167], v[168:171], v[120:123]
	s_waitcnt lgkmcnt(7)
	v_mfma_f32_16x16x32_bf16 v[116:119], v[128:131], v[168:171], v[116:119]
	v_lshl_add_u64 v[168:169], v[136:137], 0, s[18:19]
	global_load_lds_dwordx4 v[168:169], off
	v_lshl_add_u64 v[170:171], v[168:169], 0, s[22:23]
	s_mov_b32 m0, s39
	s_waitcnt lgkmcnt(6)
	v_mfma_f32_16x16x32_bf16 v[96:99], v[156:159], v[172:175], v[96:99]
	v_mfma_f32_16x16x32_bf16 v[108:111], v[160:163], v[172:175], v[108:111]
	v_mfma_f32_16x16x32_bf16 v[104:107], v[164:167], v[172:175], v[104:107]
	v_mfma_f32_16x16x32_bf16 v[100:103], v[128:131], v[172:175], v[100:103]
	global_load_lds_dwordx4 v[170:171], off
	v_lshl_add_u64 v[170:171], v[168:169], 0, s[24:25]
	s_mov_b32 m0, s38
	s_waitcnt lgkmcnt(5)
	v_mfma_f32_16x16x32_bf16 v[80:83], v[156:159], v[176:179], v[80:83]
	v_lshl_add_u64 v[168:169], v[168:169], 0, s[26:27]
	v_mfma_f32_16x16x32_bf16 v[92:95], v[160:163], v[176:179], v[92:95]
	v_mfma_f32_16x16x32_bf16 v[88:91], v[164:167], v[176:179], v[88:91]
	v_mfma_f32_16x16x32_bf16 v[84:87], v[128:131], v[176:179], v[84:87]
	global_load_lds_dwordx4 v[170:171], off
	s_mov_b32 m0, s1
	s_waitcnt lgkmcnt(4)
	v_mfma_f32_16x16x32_bf16 v[64:67], v[156:159], v[180:183], v[64:67]
	v_mfma_f32_16x16x32_bf16 v[76:79], v[160:163], v[180:183], v[76:79]
	v_mfma_f32_16x16x32_bf16 v[72:75], v[164:167], v[180:183], v[72:75]
	v_mfma_f32_16x16x32_bf16 v[68:71], v[128:131], v[180:183], v[68:71]
	global_load_lds_dwordx4 v[168:169], off
	s_waitcnt lgkmcnt(3)
	v_mfma_f32_16x16x32_bf16 v[48:51], v[156:159], v[184:187], v[48:51]
	v_mfma_f32_16x16x32_bf16 v[60:63], v[160:163], v[184:187], v[60:63]
	v_mfma_f32_16x16x32_bf16 v[56:59], v[164:167], v[184:187], v[56:59]
	v_mfma_f32_16x16x32_bf16 v[52:55], v[128:131], v[184:187], v[52:55]
	s_waitcnt lgkmcnt(2)
	v_mfma_f32_16x16x32_bf16 v[32:35], v[156:159], v[188:191], v[32:35]
	v_mfma_f32_16x16x32_bf16 v[44:47], v[160:163], v[188:191], v[44:47]
	v_mfma_f32_16x16x32_bf16 v[40:43], v[164:167], v[188:191], v[40:43]
	v_mfma_f32_16x16x32_bf16 v[36:39], v[128:131], v[188:191], v[36:39]
	s_waitcnt lgkmcnt(1)
	v_mfma_f32_16x16x32_bf16 v[12:15], v[156:159], v[192:195], v[12:15]
	v_mfma_f32_16x16x32_bf16 v[24:27], v[160:163], v[192:195], v[24:27]
	v_mfma_f32_16x16x32_bf16 v[20:23], v[164:167], v[192:195], v[20:23]
	v_mfma_f32_16x16x32_bf16 v[16:19], v[128:131], v[192:195], v[16:19]
	s_waitcnt vmcnt(0)
	s_barrier
	s_waitcnt lgkmcnt(0)
	v_mfma_f32_16x16x32_bf16 v[0:3], v[156:159], v[196:199], v[0:3]
	v_mfma_f32_16x16x32_bf16 v[8:11], v[160:163], v[196:199], v[8:11]
	v_mfma_f32_16x16x32_bf16 v[4:7], v[164:167], v[196:199], v[4:7]
	v_mfma_f32_16x16x32_bf16 v[28:31], v[128:131], v[196:199], v[28:31]
	s_cbranch_vccnz .LBB0_90
	s_lshl_b32 s5, s5, 1
	s_or_b32 s36, s5, s44
	s_cmp_gt_i32 s36, 46
	s_cbranch_scc1 .LBB0_88
	s_lshl_b32 s5, s36, 7
	s_add_i32 s6, s5, 0xfffff480
	s_cmp_lt_i32 s36, 23
	s_cselect_b32 s6, s5, s6
	s_cselect_b32 s5, s48, 0xddc5000
	s_cselect_b32 s75, s46, 0xc00
	s_add_u32 s8, s72, s5
	s_addc_u32 s9, s73, 0
	s_lshl_b32 s4, s4, 8
	s_add_i32 s4, s4, s54
	s_ashr_i32 s7, s6, 31
	v_and_or_b32 v130, v147, 15, s4
	s_lshl_b64 s[4:5], s[6:7], 1
	s_add_u32 s4, s8, s4
	s_addc_u32 s5, s9, s5
	s_add_u32 s4, s4, s49
	s_addc_u32 s5, s5, 0
	v_lshlrev_b32_e32 v132, 3, v145
	v_lshl_add_u64 v[128:129], s[4:5], 0, v[132:133]
	v_mov_b32_e32 v132, v130
	v_mad_u64_u32 v[130:131], s[4:5], s75, v130, 0
	v_lshl_add_u64 v[130:131], v[130:131], 1, v[128:129]
	v_cvt_pk_bf16_f32 v134, v112, v113
	v_cvt_pk_bf16_f32 v135, v114, v115
	s_cmp_lt_i32 s36, 6
	global_store_dwordx2 v[130:131], v[134:135], off
	v_cvt_pk_bf16_f32 v134, v124, v125
	v_cvt_pk_bf16_f32 v135, v126, v127
	s_cselect_b64 s[6:7], -1, 0
	s_cmp_lt_i32 s36, 4
	global_store_dwordx2 v[130:131], v[134:135], off offset:32
	v_cvt_pk_bf16_f32 v134, v120, v121
	v_cvt_pk_bf16_f32 v135, v122, v123
	s_cselect_b32 s18, 0, 0x8000
	s_cmp_gt_i32 s36, 5
	v_cmp_gt_u32_e64 s[8:9], 16, v146
	global_store_dwordx2 v[130:131], v[134:135], off offset:64
	v_cvt_pk_bf16_f32 v134, v116, v117
	v_cvt_pk_bf16_f32 v135, v118, v119
	global_store_dwordx2 v[130:131], v[134:135], off offset:96
	s_cbranch_scc1 .LBB0_96
	v_mul_f32_e32 v130, v113, v113
	v_mul_f32_e32 v125, v125, v125
	v_fmac_f32_e32 v130, v112, v112
	v_fmac_f32_e32 v125, v124, v124
	v_mul_f32_e32 v121, v121, v121
	v_fmac_f32_e32 v130, v114, v114
	v_fmac_f32_e32 v125, v126, v126
	v_fmac_f32_e32 v121, v120, v120
	v_mul_f32_e32 v117, v117, v117
	v_fmac_f32_e32 v130, v115, v115
	v_fmac_f32_e32 v125, v127, v127
	v_fmac_f32_e32 v121, v122, v122
	v_fmac_f32_e32 v117, v116, v116
	v_add_f32_e32 v124, v130, v125
	v_fmac_f32_e32 v121, v123, v123
	v_fmac_f32_e32 v117, v118, v118
	v_add_f32_e32 v120, v124, v121
	v_fmac_f32_e32 v117, v119, v119
	v_add_f32_e32 v116, v120, v117
	ds_bpermute_b32 v117, v144, v116
	s_waitcnt lgkmcnt(0)
	v_add_f32_e32 v116, v116, v117
	ds_bpermute_b32 v117, v241, v116
	s_and_saveexec_b64 s[4:5], s[8:9]
	s_cbranch_execz .LBB0_95
	s_lshl_b32 s37, s18, 2
	s_add_u32 s76, s12, s37
	s_addc_u32 s77, s13, 0
	s_waitcnt lgkmcnt(0)
	v_add_f32_e32 v118, v116, v117
	v_lshl_add_u64 v[116:117], v[132:133], 2, s[76:77]
	v_add_f32_e32 v118, 0x45400000, v118
	v_subrev_f32_e32 v118, 0x45400000, v118
	global_atomic_add_f32 v[116:117], v118, off

; #define MFMA(a, b, c) __builtin_amdgcn_mfma_f32_32x32x16_bf16((a), (b), (c), 0, 0, 0)
; DI int fresh_tid(const Params& p) { int t = p.wave_u * 64 + (int)__builtin_amdgcn_mbcnt_hi(~0u, __builtin_amdgcn_mbcnt_lo(~0u, 0u)); asm volatile("" : "+v"(t)); return t; }
; template <int BM, int BN, int BK, int WAVES_M, int WAVES_N, int UNSWAP_FROM>
; DI void gemm_mainloop(const int tid, const bf16_t* __restrict__ A, int lda, const bf16_t* __restrict__ Bt, int ldb, int K, unsigned char* smem,
;                       f32x16 (&acc)[BM / WAVES_M / 32][BN / WAVES_N / 32]) {
;     ...
;     const int nk = K / BK;
;     ...
;     G_LOAD(0); G_STORE(0); __syncthreads();
;     for (int kt = 0; kt < nk; ++kt) {
;         const int buf = kt & 1;
;         if (kt + 1 < nk) G_LOAD(kt + 1);
;         const unsigned char* sa_ = smem + buf * STAGE; const unsigned char* sb_ = sa_ + A_ST;
; #pragma unroll
;         for (int ks = 0; ks < BK / 16; ++ks) {
;             bf16x8 af[WM], bfr[WN];
; #pragma unroll
;             for (int i = 0; i < WM; ++i) af[i] = *(const bf16x8*)(sa_ + (((wm * WM + i) * 32 + r) * LS + ks * 16 + h * 8) * 2);
; #pragma unroll
;             for (int j = 0; j < WN; ++j) bfr[j] = *(const bf16x8*)(sb_ + (((wn * WN + j) * 32 + r) * LS + ks * 16 + h * 8) * 2);
; #pragma unroll
;             for (int i = 0; i < WM; ++i)
; #pragma unroll
;                 for (int j = 0; j < WN; ++j) {
;                     if (j < UNSWAP_FROM) acc[i][j] = MFMA(bfr[j], af[i], acc[i][j]);
;                     else acc[i][j] = MFMA(af[i], bfr[j], acc[i][j]);
;                 }
;         }
;         if (kt + 1 < nk) G_STORE(buf ^ 1);
;         __syncthreads();
; DI void q_tile(const Params& p, int mt, int hd, unsigned char* smem) {
;     ...
;     const int tid = fresh_tid(p), lane = tid & 63, wave = tid >> 6, r = lane & 31, h = lane >> 5;
;     f32x16 acc[1][6];
;     gemm_mainloop<128, 192, 32, 4, 1, 99>(tid, pa + (size_t)mt * 128 * LDPA, LDPA, wt + (size_t)hd * 192 * 512, 512, 512, smem, acc);
.LBB0_161:
	s_andn2_b64 vcc, exec, s[4:5]
	s_cbranch_vccnz .LBB0_163
	s_add_i32 s4, s51, 0xfffff000
	v_mov_b32_e32 v116, v227
	s_lshr_b32 s4, s4, 3
	s_mul_i32 s44, s4, 0x5c000
	v_ashrrev_i32_e32 v0, 31, v116
	v_lshrrev_b32_e32 v0, 30, v0
	s_lshl_b64 s[74:75], s[44:45], 1
	v_add_u32_e32 v0, v116, v0
	v_add_u32_e32 v6, 0x100, v116
	s_add_u32 s74, s8, s74
	v_ashrrev_i32_e32 v20, 2, v0
	v_and_b32_e32 v0, -4, v0
	v_ashrrev_i32_e32 v7, 31, v6
	v_add_u32_e32 v16, 0x200, v116
	s_addc_u32 s75, s9, s75
	s_mul_i32 s5, s15, 0x30000
	v_readlane_b32 s44, v244, 33
	v_sub_u32_e32 v26, v116, v0
	v_lshrrev_b32_e32 v7, 30, v7
	v_ashrrev_i32_e32 v17, 31, v16
	s_add_u32 s76, s44, s5
	v_readlane_b32 s5, v244, 34
	v_lshlrev_b32_e32 v2, 3, v26
	v_add_u32_e32 v7, v6, v7
	v_lshrrev_b32_e32 v17, 30, v17
	s_addc_u32 s77, s5, 0
	v_mov_b64_e32 v[4:5], s[74:75]
	s_movk_i32 s5, 0x1700
	v_ashrrev_i32_e32 v3, 31, v2
	v_ashrrev_i32_e32 v22, 2, v7
	v_and_b32_e32 v7, -4, v7
	v_add_u32_e32 v17, v16, v17
	v_ashrrev_i32_e32 v21, 31, v20
	v_mad_i64_i32 v[0:1], s[74:75], v20, s5, v[4:5]
	v_lshlrev_b64 v[8:9], 1, v[2:3]
	v_sub_u32_e32 v27, v6, v7
	v_ashrrev_i32_e32 v24, 2, v17
	v_and_b32_e32 v17, -4, v17
	v_lshl_add_u64 v[120:121], v[0:1], 0, v[8:9]
	v_lshlrev_b32_e32 v6, 3, v27
	v_lshlrev_b64 v[10:11], 10, v[20:21]
	v_sub_u32_e32 v21, v16, v17
	v_ashrrev_i32_e32 v25, 31, v24
	global_load_dwordx4 v[0:3], v[120:121], off
	v_ashrrev_i32_e32 v7, 31, v6
	v_lshlrev_b64 v[16:17], 10, v[24:25]
	v_lshlrev_b32_e32 v18, 3, v21
	v_ashrrev_i32_e32 v23, 31, v22
	v_mad_i64_i32 v[4:5], s[74:75], v22, s5, v[4:5]
	v_lshlrev_b64 v[12:13], 1, v[6:7]
	v_lshl_add_u64 v[16:17], s[76:77], 0, v[16:17]
	v_ashrrev_i32_e32 v19, 31, v18
	v_lshl_add_u64 v[122:123], v[4:5], 0, v[12:13]
	v_lshl_add_u64 v[10:11], s[76:77], 0, v[10:11]
	v_lshlrev_b64 v[14:15], 10, v[22:23]
	v_lshl_add_u64 v[128:129], v[18:19], 1, v[16:17]
	global_load_dwordx4 v[4:7], v[122:123], off
	v_lshl_add_u64 v[124:125], v[10:11], 0, v[8:9]
	v_lshl_add_u64 v[14:15], s[76:77], 0, v[14:15]
	global_load_dwordx4 v[16:19], v[128:129], off
	global_load_dwordx4 v[8:11], v[124:125], off
	v_lshl_add_u64 v[126:127], v[14:15], 0, v[12:13]
	global_load_dwordx4 v[12:15], v[126:127], off
	s_movk_i32 s5, 0x50
	v_lshlrev_b32_e32 v23, 4, v26
	v_mul_lo_u32 v20, v20, s5
	v_add3_u32 v130, v23, v20, s10
	v_and_b32_e32 v119, 31, v116
	s_mov_b32 s44, 0xfffffe0
	s_waitcnt vmcnt(4)
	ds_write_b128 v130, v[0:3]
	v_lshlrev_b32_e32 v0, 4, v27
	v_mul_lo_u32 v1, v22, s5
	v_add3_u32 v131, v0, v1, s10
	v_lshlrev_b32_e32 v0, 4, v21
	v_mul_lo_u32 v1, v24, s5
	v_add3_u32 v132, v0, v1, s10
	s_waitcnt vmcnt(3)
	ds_write_b128 v131, v[4:7]
	s_waitcnt vmcnt(1)
	ds_write_b128 v130, v[8:11] offset:10240
	s_waitcnt vmcnt(0)
	ds_write_b128 v131, v[12:15] offset:10240
	ds_write_b128 v132, v[16:19] offset:10240
	s_waitcnt lgkmcnt(0)
	s_barrier
	global_load_dwordx4 v[96:99], v[120:121], off offset:64
	global_load_dwordx4 v[100:103], v[122:123], off offset:64
	global_load_dwordx4 v[104:107], v[124:125], off offset:64
	global_load_dwordx4 v[108:111], v[126:127], off offset:64
	global_load_dwordx4 v[112:115], v[128:129], off offset:64
	v_lshrrev_b32_e32 v0, 1, v116
	v_and_or_b32 v1, v0, s44, v119
	v_and_b32_e32 v0, 16, v0
	v_mul_u32_u24_e32 v2, 0x50, v119
	v_mul_lo_u32 v1, v1, s5
	v_add3_u32 v133, v0, v2, s10
	v_add3_u32 v134, v1, v0, s10
	ds_read_b128 v[0:3], v133 offset:12800
	ds_read_b128 v[4:7], v133 offset:15360
	ds_read_b128 v[8:11], v133 offset:17920
	ds_read_b128 v[12:15], v133 offset:20480
	ds_read_b128 v[16:19], v133 offset:23040
	ds_read_b128 v[20:23], v134
	ds_read_b128 v[136:139], v134 offset:32
	ds_read_b128 v[24:27], v133 offset:10240
	ds_read_b128 v[140:143], v133 offset:10272
	ds_read_b128 v[144:147], v133 offset:12832
	ds_read_b128 v[148:151], v133 offset:15392
	ds_read_b128 v[152:155], v133 offset:17952
	ds_read_b128 v[156:159], v133 offset:20512
	ds_read_b128 v[160:163], v133 offset:23072
	s_waitcnt lgkmcnt(6)
	v_mfma_f32_32x32x16_bf16 v[80:95], v[24:27], v[20:23], 0
	s_waitcnt vmcnt(4)
	ds_write_b128 v130, v[96:99] offset:25600
	s_waitcnt vmcnt(3)
	ds_write_b128 v131, v[100:103] offset:25600
	s_waitcnt vmcnt(2)
	ds_write_b128 v130, v[104:107] offset:35840
	s_waitcnt vmcnt(1)
	ds_write_b128 v131, v[108:111] offset:35840
	s_waitcnt vmcnt(0)
	ds_write_b128 v132, v[112:115] offset:35840
	s_waitcnt lgkmcnt(0)
	s_barrier
	global_load_dwordx4 v[96:99], v[120:121], off offset:128
	global_load_dwordx4 v[100:103], v[122:123], off offset:128
	global_load_dwordx4 v[104:107], v[124:125], off offset:128
	global_load_dwordx4 v[108:111], v[126:127], off offset:128
	global_load_dwordx4 v[112:115], v[128:129], off offset:128
	v_mfma_f32_32x32x16_bf16 v[64:79], v[0:3], v[20:23], 0
	v_mfma_f32_32x32x16_bf16 v[48:63], v[4:7], v[20:23], 0
	v_mfma_f32_32x32x16_bf16 v[32:47], v[8:11], v[20:23], 0
	v_mfma_f32_32x32x16_bf16 v[0:15], v[12:15], v[20:23], 0
	v_mfma_f32_32x32x16_bf16 v[16:31], v[16:19], v[20:23], 0
	v_mfma_f32_32x32x16_bf16 v[64:79], v[144:147], v[136:139], v[64:79]
	v_mfma_f32_32x32x16_bf16 v[48:63], v[148:151], v[136:139], v[48:63]
	v_mfma_f32_32x32x16_bf16 v[32:47], v[152:155], v[136:139], v[32:47]
	v_mfma_f32_32x32x16_bf16 v[0:15], v[156:159], v[136:139], v[0:15]
	v_mfma_f32_32x32x16_bf16 v[16:31], v[160:163], v[136:139], v[16:31]
	v_mfma_f32_32x32x16_bf16 v[80:95], v[140:143], v[136:139], v[80:95]
	ds_read_b128 v[136:139], v133 offset:38400
	ds_read_b128 v[140:143], v133 offset:40960
	ds_read_b128 v[144:147], v133 offset:43520
	ds_read_b128 v[148:151], v133 offset:46080
	ds_read_b128 v[152:155], v133 offset:48640
	ds_read_b128 v[156:159], v134 offset:25600
	ds_read_b128 v[160:163], v134 offset:25632
	ds_read_b128 v[164:167], v133 offset:35840
	ds_read_b128 v[168:171], v133 offset:35872
	s_waitcnt lgkmcnt(3)
	v_mfma_f32_32x32x16_bf16 v[64:79], v[136:139], v[156:159], v[64:79]
	v_mfma_f32_32x32x16_bf16 v[48:63], v[140:143], v[156:159], v[48:63]
	v_mfma_f32_32x32x16_bf16 v[32:47], v[144:147], v[156:159], v[32:47]
	v_mfma_f32_32x32x16_bf16 v[0:15], v[148:151], v[156:159], v[0:15]
	v_mfma_f32_32x32x16_bf16 v[16:31], v[152:155], v[156:159], v[16:31]
	ds_read_b128 v[136:139], v133 offset:38432
	ds_read_b128 v[140:143], v133 offset:40992
	ds_read_b128 v[144:147], v133 offset:43552
	ds_read_b128 v[148:151], v133 offset:46112
	ds_read_b128 v[152:155], v133 offset:48672
	s_waitcnt vmcnt(4)
	ds_write_b128 v130, v[96:99]
	s_waitcnt vmcnt(3)
	ds_write_b128 v131, v[100:103]
	s_waitcnt vmcnt(2)
	ds_write_b128 v130, v[104:107] offset:10240
	s_waitcnt vmcnt(1)
	ds_write_b128 v131, v[108:111] offset:10240
	s_waitcnt vmcnt(0)
	ds_write_b128 v132, v[112:115] offset:10240
	s_waitcnt lgkmcnt(0)
	s_barrier
	s_mov_b64 s[100:101], 0x80
	s_movk_i32 s99, 6
; #define MFMA(a, b, c) __builtin_amdgcn_mfma_f32_32x32x16_bf16((a), (b), (c), 0, 0, 0)
; template <int BM, int BN, int BK, int WAVES_M, int WAVES_N, int UNSWAP_FROM>
; DI void gemm_mainloop(const int tid, const bf16_t* __restrict__ A, int lda, const bf16_t* __restrict__ Bt, int ldb, int K, unsigned char* smem,
;                       f32x16 (&acc)[BM / WAVES_M / 32][BN / WAVES_N / 32]) {
;     ...
;     for (int kt = 0; kt < nk; ++kt) {
;         const int buf = kt & 1;
;         if (kt + 1 < nk) G_LOAD(kt + 1);
;         const unsigned char* sa_ = smem + buf * STAGE; const unsigned char* sb_ = sa_ + A_ST;
; #pragma unroll
;         for (int ks = 0; ks < BK / 16; ++ks) {
;             bf16x8 af[WM], bfr[WN];
; #pragma unroll
;             for (int i = 0; i < WM; ++i) af[i] = *(const bf16x8*)(sa_ + (((wm * WM + i) * 32 + r) * LS + ks * 16 + h * 8) * 2);
; #pragma unroll
;             for (int j = 0; j < WN; ++j) bfr[j] = *(const bf16x8*)(sb_ + (((wn * WN + j) * 32 + r) * LS + ks * 16 + h * 8) * 2);
; #pragma unroll
;             for (int i = 0; i < WM; ++i)
; #pragma unroll
;                 for (int j = 0; j < WN; ++j) {
;                     if (j < UNSWAP_FROM) acc[i][j] = MFMA(bfr[j], af[i], acc[i][j]);
;                     else acc[i][j] = MFMA(af[i], bfr[j], acc[i][j]);
;                 }
;         }
;         if (kt + 1 < nk) G_STORE(buf ^ 1);
;         __syncthreads();
.Lq_roll:
	global_load_dwordx4 v[96:99], v[120:121], off offset:192
	global_load_dwordx4 v[100:103], v[122:123], off offset:192
	global_load_dwordx4 v[104:107], v[124:125], off offset:192
	global_load_dwordx4 v[108:111], v[126:127], off offset:192
	global_load_dwordx4 v[112:115], v[128:129], off offset:192
	v_mfma_f32_32x32x16_bf16 v[80:95], v[164:167], v[156:159], v[80:95]
	v_mfma_f32_32x32x16_bf16 v[64:79], v[136:139], v[160:163], v[64:79]
	v_mfma_f32_32x32x16_bf16 v[48:63], v[140:143], v[160:163], v[48:63]
	v_mfma_f32_32x32x16_bf16 v[32:47], v[144:147], v[160:163], v[32:47]
	v_mfma_f32_32x32x16_bf16 v[0:15], v[148:151], v[160:163], v[0:15]
	v_mfma_f32_32x32x16_bf16 v[16:31], v[152:155], v[160:163], v[16:31]
	v_mfma_f32_32x32x16_bf16 v[80:95], v[168:171], v[160:163], v[80:95]
	ds_read_b128 v[136:139], v133 offset:12800
	ds_read_b128 v[140:143], v133 offset:15360
	ds_read_b128 v[144:147], v133 offset:17920
	ds_read_b128 v[148:151], v133 offset:20480
	ds_read_b128 v[152:155], v133 offset:23040
	ds_read_b128 v[156:159], v134
	ds_read_b128 v[160:163], v134 offset:32
	ds_read_b128 v[164:167], v133 offset:10240
	ds_read_b128 v[168:171], v133 offset:10272
	s_waitcnt lgkmcnt(3)
	v_mfma_f32_32x32x16_bf16 v[64:79], v[136:139], v[156:159], v[64:79]
	v_mfma_f32_32x32x16_bf16 v[48:63], v[140:143], v[156:159], v[48:63]
	v_mfma_f32_32x32x16_bf16 v[32:47], v[144:147], v[156:159], v[32:47]
	v_mfma_f32_32x32x16_bf16 v[0:15], v[148:151], v[156:159], v[0:15]
	v_mfma_f32_32x32x16_bf16 v[16:31], v[152:155], v[156:159], v[16:31]
	ds_read_b128 v[136:139], v133 offset:12832
	ds_read_b128 v[140:143], v133 offset:15392
	ds_read_b128 v[144:147], v133 offset:17952
	ds_read_b128 v[148:151], v133 offset:20512
	ds_read_b128 v[152:155], v133 offset:23072
	s_waitcnt vmcnt(4)
	ds_write_b128 v130, v[96:99] offset:25600
	s_waitcnt vmcnt(3)
	ds_write_b128 v131, v[100:103] offset:25600
	s_waitcnt vmcnt(2)
	ds_write_b128 v130, v[104:107] offset:35840
	s_waitcnt vmcnt(1)
	ds_write_b128 v131, v[108:111] offset:35840
	s_waitcnt vmcnt(0)
	ds_write_b128 v132, v[112:115] offset:35840
	s_waitcnt lgkmcnt(0)
	s_barrier
	global_load_dwordx4 v[96:99], v[120:121], off offset:256
	global_load_dwordx4 v[100:103], v[122:123], off offset:256
	global_load_dwordx4 v[104:107], v[124:125], off offset:256
	global_load_dwordx4 v[108:111], v[126:127], off offset:256
	global_load_dwordx4 v[112:115], v[128:129], off offset:256
	v_mfma_f32_32x32x16_bf16 v[80:95], v[164:167], v[156:159], v[80:95]
	v_mfma_f32_32x32x16_bf16 v[64:79], v[136:139], v[160:163], v[64:79]
	v_mfma_f32_32x32x16_bf16 v[48:63], v[140:143], v[160:163], v[48:63]
	v_mfma_f32_32x32x16_bf16 v[32:47], v[144:147], v[160:163], v[32:47]
	v_mfma_f32_32x32x16_bf16 v[0:15], v[148:151], v[160:163], v[0:15]
	v_mfma_f32_32x32x16_bf16 v[16:31], v[152:155], v[160:163], v[16:31]
	v_mfma_f32_32x32x16_bf16 v[80:95], v[168:171], v[160:163], v[80:95]
	ds_read_b128 v[136:139], v133 offset:38400
	ds_read_b128 v[140:143], v133 offset:40960
	ds_read_b128 v[144:147], v133 offset:43520
	ds_read_b128 v[148:151], v133 offset:46080
	ds_read_b128 v[152:155], v133 offset:48640
	ds_read_b128 v[156:159], v134 offset:25600
	ds_read_b128 v[160:163], v134 offset:25632
	ds_read_b128 v[164:167], v133 offset:35840
	ds_read_b128 v[168:171], v133 offset:35872
	s_waitcnt lgkmcnt(3)
	v_mfma_f32_32x32x16_bf16 v[64:79], v[136:139], v[156:159], v[64:79]
	v_mfma_f32_32x32x16_bf16 v[48:63], v[140:143], v[156:159], v[48:63]
	v_mfma_f32_32x32x16_bf16 v[32:47], v[144:147], v[156:159], v[32:47]
	v_mfma_f32_32x32x16_bf16 v[0:15], v[148:151], v[156:159], v[0:15]
	v_mfma_f32_32x32x16_bf16 v[16:31], v[152:155], v[156:159], v[16:31]
	ds_read_b128 v[136:139], v133 offset:38432
	ds_read_b128 v[140:143], v133 offset:40992
	ds_read_b128 v[144:147], v133 offset:43552
	ds_read_b128 v[148:151], v133 offset:46112
	ds_read_b128 v[152:155], v133 offset:48672
	s_waitcnt vmcnt(4)
	ds_write_b128 v130, v[96:99]
	s_waitcnt vmcnt(3)
	ds_write_b128 v131, v[100:103]
	s_waitcnt vmcnt(2)
	ds_write_b128 v130, v[104:107] offset:10240
	s_waitcnt vmcnt(1)
	ds_write_b128 v131, v[108:111] offset:10240
	s_waitcnt vmcnt(0)
	ds_write_b128 v132, v[112:115] offset:10240
	s_waitcnt lgkmcnt(0)
	v_lshl_add_u64 v[120:121], v[120:121], 0, s[100:101]
	v_lshl_add_u64 v[122:123], v[122:123], 0, s[100:101]
	v_lshl_add_u64 v[124:125], v[124:125], 0, s[100:101]
	v_lshl_add_u64 v[126:127], v[126:127], 0, s[100:101]
	v_lshl_add_u64 v[128:129], v[128:129], 0, s[100:101]
	s_barrier
	s_add_i32 s99, s99, -1
	s_cmp_lg_u32 s99, 0
	s_cbranch_scc1 .Lq_roll
; #define MFMA(a, b, c) __builtin_amdgcn_mfma_f32_32x32x16_bf16((a), (b), (c), 0, 0, 0)
; template <int BM, int BN, int BK, int WAVES_M, int WAVES_N, int UNSWAP_FROM>
; DI void gemm_mainloop(const int tid, const bf16_t* __restrict__ A, int lda, const bf16_t* __restrict__ Bt, int ldb, int K, unsigned char* smem,
;                       f32x16 (&acc)[BM / WAVES_M / 32][BN / WAVES_N / 32]) {
;     ...
;     for (int kt = 0; kt < nk; ++kt) {
;         const int buf = kt & 1;
;         if (kt + 1 < nk) G_LOAD(kt + 1);
;         const unsigned char* sa_ = smem + buf * STAGE; const unsigned char* sb_ = sa_ + A_ST;
; #pragma unroll
;         for (int ks = 0; ks < BK / 16; ++ks) {
;             bf16x8 af[WM], bfr[WN];
; #pragma unroll
;             for (int i = 0; i < WM; ++i) af[i] = *(const bf16x8*)(sa_ + (((wm * WM + i) * 32 + r) * LS + ks * 16 + h * 8) * 2);
; #pragma unroll
;             for (int j = 0; j < WN; ++j) bfr[j] = *(const bf16x8*)(sb_ + (((wn * WN + j) * 32 + r) * LS + ks * 16 + h * 8) * 2);
; #pragma unroll
;             for (int i = 0; i < WM; ++i)
; #pragma unroll
;                 for (int j = 0; j < WN; ++j) {
;                     if (j < UNSWAP_FROM) acc[i][j] = MFMA(bfr[j], af[i], acc[i][j]);
;                     else acc[i][j] = MFMA(af[i], bfr[j], acc[i][j]);
;                 }
;         }
;         if (kt + 1 < nk) G_STORE(buf ^ 1);
;         __syncthreads();
; DI void q_tile(const Params& p, int mt, int hd, unsigned char* smem) {
;     ...
;     const int m = mt * 128 + wave * 32 + r;
;     const float rq = rsqrtf(ssq[m] * (1.f / 512.f) + EPS);
	s_mov_b32 s100, 0xfffffd00
	s_mov_b32 s101, -1
	v_lshl_add_u64 v[120:121], v[120:121], 0, s[100:101]
	v_lshl_add_u64 v[122:123], v[122:123], 0, s[100:101]
	v_lshl_add_u64 v[124:125], v[124:125], 0, s[100:101]
	v_lshl_add_u64 v[126:127], v[126:127], 0, s[100:101]
	v_lshl_add_u64 v[128:129], v[128:129], 0, s[100:101]
	global_load_dwordx4 v[96:99], v[120:121], off offset:960
	global_load_dwordx4 v[100:103], v[122:123], off offset:960
	global_load_dwordx4 v[104:107], v[124:125], off offset:960
	global_load_dwordx4 v[108:111], v[126:127], off offset:960
	global_load_dwordx4 v[112:115], v[128:129], off offset:960
	v_mfma_f32_32x32x16_bf16 v[80:95], v[164:167], v[156:159], v[80:95]
	v_mfma_f32_32x32x16_bf16 v[64:79], v[136:139], v[160:163], v[64:79]
	v_mfma_f32_32x32x16_bf16 v[48:63], v[140:143], v[160:163], v[48:63]
	v_mfma_f32_32x32x16_bf16 v[80:95], v[168:171], v[160:163], v[80:95]
	v_mfma_f32_32x32x16_bf16 v[32:47], v[144:147], v[160:163], v[32:47]
	v_mfma_f32_32x32x16_bf16 v[0:15], v[148:151], v[160:163], v[0:15]
	v_mfma_f32_32x32x16_bf16 v[16:31], v[152:155], v[160:163], v[16:31]
	ds_read_b128 v[120:123], v133 offset:12800
	ds_read_b128 v[124:127], v133 offset:15360
	ds_read_b128 v[136:139], v133 offset:17920
	ds_read_b128 v[140:143], v133 offset:20480
	ds_read_b128 v[144:147], v133 offset:23040
	ds_read_b128 v[148:151], v134
	ds_read_b128 v[152:155], v134 offset:32
	ds_read_b128 v[156:159], v133 offset:10240
	ds_read_b128 v[160:163], v133 offset:10272
	s_waitcnt lgkmcnt(3)
	v_mfma_f32_32x32x16_bf16 v[64:79], v[120:123], v[148:151], v[64:79]
	v_mfma_f32_32x32x16_bf16 v[48:63], v[124:127], v[148:151], v[48:63]
	s_waitcnt lgkmcnt(1)
	v_mfma_f32_32x32x16_bf16 v[80:95], v[156:159], v[148:151], v[80:95]
	v_mfma_f32_32x32x16_bf16 v[32:47], v[136:139], v[148:151], v[32:47]
	v_mfma_f32_32x32x16_bf16 v[0:15], v[140:143], v[148:151], v[0:15]
	v_mfma_f32_32x32x16_bf16 v[16:31], v[144:147], v[148:151], v[16:31]
	ds_read_b128 v[120:123], v133 offset:12832
	ds_read_b128 v[124:127], v133 offset:15392
	ds_read_b128 v[136:139], v133 offset:17952
	ds_read_b128 v[140:143], v133 offset:20512
	ds_read_b128 v[144:147], v133 offset:23072
	s_waitcnt vmcnt(4)
	ds_write_b128 v130, v[96:99] offset:25600
	s_waitcnt vmcnt(3)
	ds_write_b128 v131, v[100:103] offset:25600
	s_waitcnt vmcnt(2)
	ds_write_b128 v130, v[104:107] offset:35840
	s_waitcnt vmcnt(1)
	ds_write_b128 v131, v[108:111] offset:35840
	s_waitcnt vmcnt(0)
	ds_write_b128 v132, v[112:115] offset:35840
	s_waitcnt lgkmcnt(0)
	s_barrier
	v_mfma_f32_32x32x16_bf16 v[64:79], v[120:123], v[152:155], v[64:79]
	v_mfma_f32_32x32x16_bf16 v[48:63], v[124:127], v[152:155], v[48:63]
	v_mfma_f32_32x32x16_bf16 v[80:95], v[160:163], v[152:155], v[80:95]
	v_mfma_f32_32x32x16_bf16 v[32:47], v[136:139], v[152:155], v[32:47]
	ds_read_b128 v[96:99], v133 offset:38400
	ds_read_b128 v[100:103], v133 offset:40960
	ds_read_b128 v[104:107], v133 offset:43520
	ds_read_b128 v[108:111], v133 offset:46080
	ds_read_b128 v[112:115], v133 offset:48640
	ds_read_b128 v[120:123], v134 offset:25600
	ds_read_b128 v[124:127], v134 offset:25632
	ds_read_b128 v[128:131], v133 offset:35840
	ds_read_b128 v[134:137], v133 offset:35872
	v_mfma_f32_32x32x16_bf16 v[0:15], v[140:143], v[152:155], v[0:15]
	v_mfma_f32_32x32x16_bf16 v[16:31], v[144:147], v[152:155], v[16:31]
	s_waitcnt lgkmcnt(3)
	v_mfma_f32_32x32x16_bf16 v[64:79], v[96:99], v[120:123], v[64:79]
	v_mfma_f32_32x32x16_bf16 v[48:63], v[100:103], v[120:123], v[48:63]
	s_waitcnt lgkmcnt(1)
	v_mfma_f32_32x32x16_bf16 v[80:95], v[128:131], v[120:123], v[80:95]
	v_mfma_f32_32x32x16_bf16 v[32:47], v[104:107], v[120:123], v[32:47]
	v_mfma_f32_32x32x16_bf16 v[0:15], v[108:111], v[120:123], v[0:15]
	v_mfma_f32_32x32x16_bf16 v[16:31], v[112:115], v[120:123], v[16:31]
	ds_read_b128 v[96:99], v133 offset:38432
	ds_read_b128 v[100:103], v133 offset:40992
	ds_read_b128 v[104:107], v133 offset:43552
	ds_read_b128 v[108:111], v133 offset:46112
	ds_read_b128 v[112:115], v133 offset:48672
	s_waitcnt lgkmcnt(0)
	s_barrier
	v_mfma_f32_32x32x16_bf16 v[64:79], v[96:99], v[124:127], v[64:79]
	v_ashrrev_i32_e32 v96, 1, v116
	v_and_b32_e32 v96, 0xffffffe0, v96
	v_mfma_f32_32x32x16_bf16 v[48:63], v[100:103], v[124:127], v[48:63]
	v_lshl_add_u32 v102, s4, 7, v96
	v_or_b32_e32 v100, v102, v119
	v_ashrrev_i32_e32 v101, 31, v100
	s_movk_i32 s4, 0x1fff
	v_mfma_f32_32x32x16_bf16 v[80:95], v[134:137], v[124:127], v[80:95]
	v_mfma_f32_32x32x16_bf16 v[32:47], v[104:107], v[124:127], v[32:47]
	v_mfma_f32_32x32x16_bf16 v[0:15], v[108:111], v[124:127], v[0:15]
	v_mfma_f32_32x32x16_bf16 v[16:31], v[112:115], v[124:127], v[16:31]
	v_lshlrev_b64 v[124:125], 2, v[100:101]
	v_lshl_add_u64 v[96:97], s[12:13], 0, v[124:125]
	global_load_dword v96, v[96:97], off
	s_waitcnt vmcnt(0)
; DI void q_tile(const Params& p, int mt, int hd, unsigned char* smem) {
;     ...
;     const int m = mt * 128 + wave * 32 + r;
;     const float rq = rsqrtf(ssq[m] * (1.f / 512.f) + EPS);
;     float ss = 0.f;
; #pragma unroll
;     for (int j = 0; j < 6; ++j)
; #pragma unroll
;         for (int e = 0; e < 16; ++e) { const float v = acc[0][j][e] * rq; acc[0][j][e] = v; ss += v * v; }
;     ss += __shfl_xor(ss, 32);
;     const float rs = rsqrtf(ss * (1.f / 192.f) + EPS) * QSCALE;
;     const int bb = m >> 13, s = m & 8191;
;     bf16_t* qrow = Q + ((size_t)(bb * 8 + hd) * SEQ_ + s) * 192;
; #pragma unroll
;     for (int j = 0; j < 4; ++j)
; #pragma unroll
;         for (int g = 0; g < 4; ++g) {
;             const int n = j * 32 + 8 * g + 4 * h;
;             const f32x4 gn = *(const f32x4*)(p.q_gain + n);
	v_fmamk_f32 v96, v96, 0x3b000000, v202
	v_cmp_gt_f32_e32 vcc, s53, v96
	v_mul_f32_e32 v97, 0x4b800000, v96
	s_nop 0
	v_cndmask_b32_e32 v96, v96, v97, vcc
	v_rsq_f32_e32 v96, v96
	s_nop 0
	v_mul_f32_e32 v97, 0x45800000, v96
	v_cndmask_b32_e32 v122, v96, v97, vcc
	v_pk_mul_f32 v[98:99], v[28:29], v[122:123] op_sel_hi:[1,0]
	v_ashrrev_i32_e32 v28, 10, v102
	v_and_or_b32 v28, v28, -8, s15
	v_ashrrev_i32_e32 v29, 31, v28
	v_lshlrev_b64 v[28:29], 13, v[28:29]
	v_and_or_b32 v28, v100, s4, v28
	v_readlane_b32 s4, v244, 35
	v_readlane_b32 s5, v244, 36
	v_pk_mul_f32 v[96:97], v[30:31], v[122:123] op_sel_hi:[1,0]
	s_movk_i32 s15, 0x180
	v_mov_b64_e32 v[30:31], s[4:5]
	v_mad_u64_u32 v[100:101], s[4:5], v28, s15, v[30:31]
	v_lshrrev_b32_e32 v28, 3, v116
	v_and_b32_e32 v102, 4, v28
	v_pk_mul_f32 v[114:115], v[80:81], v[122:123] op_sel_hi:[1,0]
	v_mad_i32_i24 v101, v29, s15, v101
	v_pk_mul_f32 v[106:107], v[82:83], v[122:123] op_sel_hi:[1,0]
	v_pk_mul_f32 v[128:129], v[114:115], v[114:115]
	v_lshlrev_b32_e32 v116, 1, v102
	v_pk_mul_f32 v[126:127], v[106:107], v[106:107]
	v_lshl_add_u64 v[80:81], v[100:101], 0, v[116:117]
	v_add_f32_e32 v116, v128, v129
	v_pk_mul_f32 v[120:121], v[84:85], v[122:123] op_sel_hi:[1,0]
	v_add_f32_e32 v116, v126, v116
	v_pk_mul_f32 v[132:133], v[120:121], v[120:121]
	v_add_f32_e32 v116, v127, v116
	v_pk_mul_f32 v[112:113], v[86:87], v[122:123] op_sel_hi:[1,0]
	v_add_f32_e32 v116, v132, v116
	v_pk_mul_f32 v[130:131], v[112:113], v[112:113]
	v_add_f32_e32 v116, v133, v116
	v_pk_mul_f32 v[110:111], v[88:89], v[122:123] op_sel_hi:[1,0]
	v_add_f32_e32 v116, v130, v116
	v_pk_mul_f32 v[136:137], v[110:111], v[110:111]
	v_add_f32_e32 v116, v131, v116
	v_lshlrev_b32_e32 v119, 2, v102
	v_pk_mul_f32 v[102:103], v[90:91], v[122:123] op_sel_hi:[1,0]
	v_add_f32_e32 v116, v136, v116
	v_pk_mul_f32 v[134:135], v[102:103], v[102:103]
	v_add_f32_e32 v116, v137, v116
	v_pk_mul_f32 v[100:101], v[92:93], v[122:123] op_sel_hi:[1,0]
	v_add_f32_e32 v116, v134, v116
	v_pk_mul_f32 v[140:141], v[100:101], v[100:101]
	v_add_f32_e32 v116, v135, v116
	v_pk_mul_f32 v[94:95], v[94:95], v[122:123] op_sel_hi:[1,0]
	v_add_f32_e32 v116, v140, v116
	v_pk_mul_f32 v[138:139], v[94:95], v[94:95]
	v_add_f32_e32 v116, v141, v116
	v_pk_mul_f32 v[92:93], v[64:65], v[122:123] op_sel_hi:[1,0]
	v_add_f32_e32 v116, v138, v116
	v_pk_mul_f32 v[144:145], v[92:93], v[92:93]
	v_add_f32_e32 v116, v139, v116
	v_pk_mul_f32 v[90:91], v[66:67], v[122:123] op_sel_hi:[1,0]
	v_add_f32_e32 v116, v144, v116
	v_pk_mul_f32 v[142:143], v[90:91], v[90:91]
	v_add_f32_e32 v116, v145, v116
	v_pk_mul_f32 v[88:89], v[68:69], v[122:123] op_sel_hi:[1,0]
	v_add_f32_e32 v116, v142, v116
	v_pk_mul_f32 v[148:149], v[88:89], v[88:89]
	v_add_f32_e32 v116, v143, v116
	v_pk_mul_f32 v[86:87], v[70:71], v[122:123] op_sel_hi:[1,0]
	v_add_f32_e32 v116, v148, v116
	v_pk_mul_f32 v[146:147], v[86:87], v[86:87]
	v_add_f32_e32 v116, v149, v116
	v_pk_mul_f32 v[84:85], v[72:73], v[122:123] op_sel_hi:[1,0]
	v_add_f32_e32 v116, v146, v116
	v_pk_mul_f32 v[152:153], v[84:85], v[84:85]
	v_add_f32_e32 v116, v147, v116
	v_pk_mul_f32 v[82:83], v[74:75], v[122:123] op_sel_hi:[1,0]
	v_add_f32_e32 v116, v152, v116
	v_pk_mul_f32 v[150:151], v[82:83], v[82:83]
	v_add_f32_e32 v116, v153, v116
	v_pk_mul_f32 v[76:77], v[76:77], v[122:123] op_sel_hi:[1,0]
	v_add_f32_e32 v116, v150, v116
	v_pk_mul_f32 v[156:157], v[76:77], v[76:77]
	v_add_f32_e32 v116, v151, v116
	v_pk_mul_f32 v[78:79], v[78:79], v[122:123] op_sel_hi:[1,0]
	v_add_f32_e32 v116, v156, v116
	v_pk_mul_f32 v[154:155], v[78:79], v[78:79]
	v_add_f32_e32 v116, v157, v116
	v_pk_mul_f32 v[74:75], v[48:49], v[122:123] op_sel_hi:[1,0]
	v_add_f32_e32 v116, v154, v116
	v_pk_mul_f32 v[160:161], v[74:75], v[74:75]
	v_add_f32_e32 v116, v155, v116
	v_pk_mul_f32 v[72:73], v[50:51], v[122:123] op_sel_hi:[1,0]
	v_add_f32_e32 v116, v160, v116
	global_load_dwordx4 v[28:31], v119, s[56:57]
	v_pk_mul_f32 v[158:159], v[72:73], v[72:73]
	v_add_f32_e32 v116, v161, v116
	v_pk_mul_f32 v[70:71], v[52:53], v[122:123] op_sel_hi:[1,0]
	v_add_f32_e32 v116, v158, v116
	v_pk_mul_f32 v[164:165], v[70:71], v[70:71]
	v_add_f32_e32 v116, v159, v116
	v_pk_mul_f32 v[68:69], v[54:55], v[122:123] op_sel_hi:[1,0]
	v_add_f32_e32 v116, v164, v116
	v_pk_mul_f32 v[162:163], v[68:69], v[68:69]
	v_add_f32_e32 v116, v165, v116
	v_pk_mul_f32 v[66:67], v[56:57], v[122:123] op_sel_hi:[1,0]
	v_add_f32_e32 v116, v162, v116
	v_pk_mul_f32 v[168:169], v[66:67], v[66:67]
	v_add_f32_e32 v116, v163, v116
	v_pk_mul_f32 v[64:65], v[58:59], v[122:123] op_sel_hi:[1,0]
	v_add_f32_e32 v116, v168, v116
	v_pk_mul_f32 v[166:167], v[64:65], v[64:65]
	v_add_f32_e32 v116, v169, v116
	v_pk_mul_f32 v[60:61], v[60:61], v[122:123] op_sel_hi:[1,0]
	v_add_f32_e32 v116, v166, v116
	v_pk_mul_f32 v[172:173], v[60:61], v[60:61]
	v_add_f32_e32 v116, v167, v116
	v_pk_mul_f32 v[62:63], v[62:63], v[122:123] op_sel_hi:[1,0]
	v_add_f32_e32 v116, v172, v116
	v_pk_mul_f32 v[170:171], v[62:63], v[62:63]
	v_add_f32_e32 v116, v173, v116
	v_pk_mul_f32 v[58:59], v[32:33], v[122:123] op_sel_hi:[1,0]
	v_add_f32_e32 v116, v170, v116
	v_pk_mul_f32 v[176:177], v[58:59], v[58:59]
	v_add_f32_e32 v116, v171, v116
	v_pk_mul_f32 v[56:57], v[34:35], v[122:123] op_sel_hi:[1,0]
	v_add_f32_e32 v116, v176, v116
	v_pk_mul_f32 v[174:175], v[56:57], v[56:57]
	v_add_f32_e32 v116, v177, v116
	v_pk_mul_f32 v[54:55], v[36:37], v[122:123] op_sel_hi:[1,0]
	v_add_f32_e32 v116, v174, v116
	v_pk_mul_f32 v[180:181], v[54:55], v[54:55]
	v_add_f32_e32 v116, v175, v116
	v_pk_mul_f32 v[52:53], v[38:39], v[122:123] op_sel_hi:[1,0]
	v_add_f32_e32 v116, v180, v116
	v_pk_mul_f32 v[178:179], v[52:53], v[52:53]
; DI unsigned pk2(float a, float b) { f2_t v = {a, b}; bf2_t r = __builtin_convertvector(v, bf2_t); return __builtin_bit_cast(unsigned, r); }
; DI void q_tile(const Params& p, int mt, int hd, unsigned char* smem) {
;     ...
; #pragma unroll
;     for (int j = 0; j < 6; ++j)
; #pragma unroll
;         for (int e = 0; e < 16; ++e) { const float v = acc[0][j][e] * rq; acc[0][j][e] = v; ss += v * v; }
;     ss += __shfl_xor(ss, 32);
;     const float rs = rsqrtf(ss * (1.f / 192.f) + EPS) * QSCALE;
;     const int bb = m >> 13, s = m & 8191;
;     bf16_t* qrow = Q + ((size_t)(bb * 8 + hd) * SEQ_ + s) * 192;
; #pragma unroll
;     for (int j = 0; j < 4; ++j)
; #pragma unroll
;         for (int g = 0; g < 4; ++g) {
;             const int n = j * 32 + 8 * g + 4 * h;
;             const f32x4 gn = *(const f32x4*)(p.q_gain + n);
;             u32x2 o; o.x = pk2(acc[0][j][4 * g] * rs * gn.x, acc[0][j][4 * g + 1] * rs * gn.y);
;             o.y = pk2(acc[0][j][4 * g + 2] * rs * gn.z, acc[0][j][4 * g + 3] * rs * gn.w);
;             *(u32x2*)(qrow + n) = o;
;         }
	v_add_f32_e32 v116, v181, v116
	v_pk_mul_f32 v[50:51], v[40:41], v[122:123] op_sel_hi:[1,0]
	v_add_f32_e32 v116, v178, v116
	v_pk_mul_f32 v[184:185], v[50:51], v[50:51]
	v_add_f32_e32 v116, v179, v116
	v_pk_mul_f32 v[48:49], v[42:43], v[122:123] op_sel_hi:[1,0]
	v_add_f32_e32 v116, v184, v116
	v_pk_mul_f32 v[182:183], v[48:49], v[48:49]
	v_add_f32_e32 v116, v185, v116
	v_pk_mul_f32 v[44:45], v[44:45], v[122:123] op_sel_hi:[1,0]
	v_add_f32_e32 v116, v182, v116
	v_pk_mul_f32 v[188:189], v[44:45], v[44:45]
	v_add_f32_e32 v116, v183, v116
	v_pk_mul_f32 v[46:47], v[46:47], v[122:123] op_sel_hi:[1,0]
	v_add_f32_e32 v116, v188, v116
	v_pk_mul_f32 v[186:187], v[46:47], v[46:47]
	v_add_f32_e32 v116, v189, v116
	v_pk_mul_f32 v[42:43], v[0:1], v[122:123] op_sel_hi:[1,0]
	v_add_f32_e32 v116, v186, v116
	v_pk_mul_f32 v[190:191], v[42:43], v[42:43]
	v_add_f32_e32 v116, v187, v116
	v_pk_mul_f32 v[36:37], v[2:3], v[122:123] op_sel_hi:[1,0]
	v_add_f32_e32 v116, v190, v116
	v_pk_mul_f32 v[2:3], v[36:37], v[36:37]
	v_add_f32_e32 v116, v191, v116
	v_pk_mul_f32 v[34:35], v[18:19], v[122:123] op_sel_hi:[1,0]
	v_pk_mul_f32 v[18:19], v[22:23], v[122:123] op_sel_hi:[1,0]
	v_pk_mul_f32 v[22:23], v[4:5], v[122:123] op_sel_hi:[1,0]
	v_add_f32_e32 v2, v2, v116
	v_pk_mul_f32 v[214:215], v[22:23], v[22:23]
	v_add_f32_e32 v2, v3, v2
	v_pk_mul_f32 v[32:33], v[6:7], v[122:123] op_sel_hi:[1,0]
	v_add_f32_e32 v2, v214, v2
	v_pk_mul_f32 v[210:211], v[32:33], v[32:33]
	v_add_f32_e32 v2, v215, v2
	v_pk_mul_f32 v[38:39], v[16:17], v[122:123] op_sel_hi:[1,0]
	v_pk_mul_f32 v[16:17], v[8:9], v[122:123] op_sel_hi:[1,0]
	v_add_f32_e32 v2, v210, v2
	v_pk_mul_f32 v[220:221], v[16:17], v[16:17]
	v_add_f32_e32 v2, v211, v2
	v_pk_mul_f32 v[10:11], v[10:11], v[122:123] op_sel_hi:[1,0]
	v_add_f32_e32 v2, v220, v2
	v_pk_mul_f32 v[218:219], v[10:11], v[10:11]
	v_add_f32_e32 v2, v221, v2
	v_pk_mul_f32 v[4:5], v[12:13], v[122:123] op_sel_hi:[1,0]
	v_add_f32_e32 v2, v218, v2
	v_pk_mul_f32 v[12:13], v[4:5], v[4:5]
	v_add_f32_e32 v2, v219, v2
	v_pk_mul_f32 v[0:1], v[14:15], v[122:123] op_sel_hi:[1,0]
	v_add_f32_e32 v2, v12, v2
	v_pk_mul_f32 v[14:15], v[0:1], v[0:1]
	v_add_f32_e32 v2, v13, v2
	v_add_f32_e32 v2, v14, v2
	v_pk_mul_f32 v[208:209], v[38:39], v[38:39]
	v_add_f32_e32 v2, v15, v2
	v_add_f32_e32 v2, v208, v2
	v_lshl_add_u64 v[40:41], s[42:43], 0, v[124:125]
	v_pk_mul_f32 v[124:125], v[34:35], v[34:35]
	v_add_f32_e32 v2, v209, v2
	v_pk_mul_f32 v[20:21], v[20:21], v[122:123] op_sel_hi:[1,0]
	v_add_f32_e32 v2, v124, v2
	v_pk_mul_f32 v[216:217], v[20:21], v[20:21]
	v_add_f32_e32 v2, v125, v2
	v_add_f32_e32 v2, v216, v2
	v_pk_mul_f32 v[212:213], v[18:19], v[18:19]
	v_add_f32_e32 v2, v217, v2
	v_pk_mul_f32 v[8:9], v[24:25], v[122:123] op_sel_hi:[1,0]
	v_add_f32_e32 v2, v212, v2
	v_pk_mul_f32 v[24:25], v[8:9], v[8:9]
	v_add_f32_e32 v2, v213, v2
	v_pk_mul_f32 v[6:7], v[26:27], v[122:123] op_sel_hi:[1,0]
	v_add_f32_e32 v2, v24, v2
	v_pk_mul_f32 v[26:27], v[6:7], v[6:7]
	v_add_f32_e32 v2, v25, v2
	v_add_f32_e32 v2, v26, v2
	v_pk_mul_f32 v[104:105], v[98:99], v[98:99]
	v_add_f32_e32 v2, v27, v2
	v_add_f32_e32 v2, v104, v2
	v_pk_mul_f32 v[108:109], v[96:97], v[96:97]
	v_add_f32_e32 v2, v105, v2
	v_add_f32_e32 v2, v108, v2
	v_add_f32_e32 v2, v109, v2
	ds_bpermute_b32 v3, v241, v2
	s_waitcnt lgkmcnt(0)
	v_add_f32_e32 v2, v2, v3
	v_fmamk_f32 v2, v2, 0x3baaaaab, v202
	v_cmp_gt_f32_e32 vcc, s53, v2
	v_mul_f32_e32 v3, 0x4b800000, v2
	s_nop 0
	v_cndmask_b32_e32 v2, v2, v3, vcc
	v_rsq_f32_e32 v2, v2
	s_nop 0
	v_mul_f32_e32 v3, 0x45800000, v2
	v_cndmask_b32_e32 v2, v2, v3, vcc
	v_mul_f32_e32 v2, 0x3dd53b94, v2
	v_pk_mul_f32 v[12:13], v[114:115], v[2:3] op_sel_hi:[1,0]
	v_pk_mul_f32 v[14:15], v[106:107], v[2:3] op_sel_hi:[1,0]
	s_waitcnt vmcnt(0)
	v_pk_mul_f32 v[12:13], v[28:29], v[12:13]
	v_pk_mul_f32 v[14:15], v[30:31], v[14:15]
	v_cvt_pk_bf16_f32 v12, v12, v13
	v_cvt_pk_bf16_f32 v13, v14, v15
	global_store_dwordx2 v[80:81], v[12:13], off
	global_load_dwordx4 v[12:15], v119, s[56:57] offset:32
	v_pk_mul_f32 v[24:25], v[120:121], v[2:3] op_sel_hi:[1,0]
	s_waitcnt vmcnt(0)
	v_pk_mul_f32 v[12:13], v[12:13], v[24:25]
	v_pk_mul_f32 v[24:25], v[112:113], v[2:3] op_sel_hi:[1,0]
	v_cvt_pk_bf16_f32 v12, v12, v13
	v_pk_mul_f32 v[14:15], v[14:15], v[24:25]
	v_pk_mul_f32 v[24:25], v[110:111], v[2:3] op_sel_hi:[1,0]
	v_cvt_pk_bf16_f32 v13, v14, v15
	global_store_dwordx2 v[80:81], v[12:13], off offset:16
	global_load_dwordx4 v[12:15], v119, s[56:57] offset:64
	s_waitcnt vmcnt(0)
	v_pk_mul_f32 v[12:13], v[12:13], v[24:25]
	v_pk_mul_f32 v[24:25], v[102:103], v[2:3] op_sel_hi:[1,0]
	v_cvt_pk_bf16_f32 v12, v12, v13
	v_pk_mul_f32 v[14:15], v[14:15], v[24:25]
	v_pk_mul_f32 v[24:25], v[100:101], v[2:3] op_sel_hi:[1,0]
	v_cvt_pk_bf16_f32 v13, v14, v15
	global_store_dwordx2 v[80:81], v[12:13], off offset:32
	global_load_dwordx4 v[12:15], v119, s[56:57] offset:96
	s_waitcnt vmcnt(0)
	v_pk_mul_f32 v[12:13], v[12:13], v[24:25]
	v_pk_mul_f32 v[24:25], v[94:95], v[2:3] op_sel_hi:[1,0]
	v_cvt_pk_bf16_f32 v12, v12, v13
	v_pk_mul_f32 v[14:15], v[14:15], v[24:25]
	v_pk_mul_f32 v[24:25], v[92:93], v[2:3] op_sel_hi:[1,0]
	v_cvt_pk_bf16_f32 v13, v14, v15
	global_store_dwordx2 v[80:81], v[12:13], off offset:48
	global_load_dwordx4 v[12:15], v119, s[56:57] offset:128
	s_waitcnt vmcnt(0)
	v_pk_mul_f32 v[12:13], v[12:13], v[24:25]
	v_pk_mul_f32 v[24:25], v[90:91], v[2:3] op_sel_hi:[1,0]
	v_cvt_pk_bf16_f32 v12, v12, v13
	v_pk_mul_f32 v[14:15], v[14:15], v[24:25]
	v_pk_mul_f32 v[24:25], v[88:89], v[2:3] op_sel_hi:[1,0]
	v_cvt_pk_bf16_f32 v13, v14, v15
	global_store_dwordx2 v[80:81], v[12:13], off offset:64
	global_load_dwordx4 v[12:15], v119, s[56:57] offset:160
	s_waitcnt vmcnt(0)
; DI unsigned pk2(float a, float b) { f2_t v = {a, b}; bf2_t r = __builtin_convertvector(v, bf2_t); return __builtin_bit_cast(unsigned, r); }
; DI void q_tile(const Params& p, int mt, int hd, unsigned char* smem) {
;     ...
;         for (int g = 0; g < 4; ++g) {
;             const int n = j * 32 + 8 * g + 4 * h;
;             const f32x4 gn = *(const f32x4*)(p.q_gain + n);
;             u32x2 o; o.x = pk2(acc[0][j][4 * g] * rs * gn.x, acc[0][j][4 * g + 1] * rs * gn.y);
;             o.y = pk2(acc[0][j][4 * g + 2] * rs * gn.z, acc[0][j][4 * g + 3] * rs * gn.w);
;             *(u32x2*)(qrow + n) = o;
;         }
;     const float posf = (float)p.pos[m];
;     const float* invf = (const float*)(p.ws + WS_CTRL + 256);
; #pragma unroll
;     for (int g = 0; g < 4; ++g) {
;         float o1[4], o2[4];
; #pragma unroll
;         for (int jj = 0; jj < 4; ++jj) {
;             const int i = 8 * g + 4 * h + jj;
;             float sn, cs; sincos_rev(posf * invf[i], sn, cs);
;             const float x1 = acc[0][4][4 * g + jj] * rs * p.q_gain[128 + i], x2 = acc[0][5][4 * g + jj] * rs * p.q_gain[160 + i];
;             o1[jj] = x1 * cs - x2 * sn; o2[jj] = x2 * cs + x1 * sn;
;         }
	v_pk_mul_f32 v[12:13], v[12:13], v[24:25]
	v_pk_mul_f32 v[24:25], v[86:87], v[2:3] op_sel_hi:[1,0]
	v_cvt_pk_bf16_f32 v12, v12, v13
	v_pk_mul_f32 v[14:15], v[14:15], v[24:25]
	v_pk_mul_f32 v[24:25], v[84:85], v[2:3] op_sel_hi:[1,0]
	v_cvt_pk_bf16_f32 v13, v14, v15
	global_store_dwordx2 v[80:81], v[12:13], off offset:80
	global_load_dwordx4 v[12:15], v119, s[56:57] offset:192
	s_waitcnt vmcnt(0)
	v_pk_mul_f32 v[12:13], v[12:13], v[24:25]
	v_pk_mul_f32 v[24:25], v[82:83], v[2:3] op_sel_hi:[1,0]
	v_cvt_pk_bf16_f32 v12, v12, v13
	v_pk_mul_f32 v[14:15], v[14:15], v[24:25]
	v_pk_mul_f32 v[24:25], v[76:77], v[2:3] op_sel_hi:[1,0]
	v_cvt_pk_bf16_f32 v13, v14, v15
	global_store_dwordx2 v[80:81], v[12:13], off offset:96
	global_load_dwordx4 v[12:15], v119, s[56:57] offset:224
	s_waitcnt vmcnt(0)
	v_pk_mul_f32 v[12:13], v[12:13], v[24:25]
	v_pk_mul_f32 v[24:25], v[78:79], v[2:3] op_sel_hi:[1,0]
	v_cvt_pk_bf16_f32 v12, v12, v13
	v_pk_mul_f32 v[14:15], v[14:15], v[24:25]
	v_pk_mul_f32 v[24:25], v[74:75], v[2:3] op_sel_hi:[1,0]
	v_cvt_pk_bf16_f32 v13, v14, v15
	global_store_dwordx2 v[80:81], v[12:13], off offset:112
	global_load_dwordx4 v[12:15], v119, s[56:57] offset:256
	s_waitcnt vmcnt(0)
	v_pk_mul_f32 v[12:13], v[12:13], v[24:25]
	v_pk_mul_f32 v[24:25], v[72:73], v[2:3] op_sel_hi:[1,0]
	v_cvt_pk_bf16_f32 v12, v12, v13
	v_pk_mul_f32 v[14:15], v[14:15], v[24:25]
	v_pk_mul_f32 v[24:25], v[70:71], v[2:3] op_sel_hi:[1,0]
	v_cvt_pk_bf16_f32 v13, v14, v15
	global_store_dwordx2 v[80:81], v[12:13], off offset:128
	global_load_dwordx4 v[12:15], v119, s[56:57] offset:288
	s_waitcnt vmcnt(0)
	v_pk_mul_f32 v[12:13], v[12:13], v[24:25]
	v_pk_mul_f32 v[24:25], v[68:69], v[2:3] op_sel_hi:[1,0]
	v_cvt_pk_bf16_f32 v12, v12, v13
	v_pk_mul_f32 v[14:15], v[14:15], v[24:25]
	v_pk_mul_f32 v[24:25], v[66:67], v[2:3] op_sel_hi:[1,0]
	v_cvt_pk_bf16_f32 v13, v14, v15
	global_store_dwordx2 v[80:81], v[12:13], off offset:144
	global_load_dwordx4 v[12:15], v119, s[56:57] offset:320
	s_waitcnt vmcnt(0)
	v_pk_mul_f32 v[12:13], v[12:13], v[24:25]
	v_pk_mul_f32 v[24:25], v[64:65], v[2:3] op_sel_hi:[1,0]
	v_cvt_pk_bf16_f32 v12, v12, v13
	v_pk_mul_f32 v[14:15], v[14:15], v[24:25]
	v_pk_mul_f32 v[24:25], v[60:61], v[2:3] op_sel_hi:[1,0]
	v_cvt_pk_bf16_f32 v13, v14, v15
	global_store_dwordx2 v[80:81], v[12:13], off offset:160
	global_load_dwordx4 v[12:15], v119, s[56:57] offset:352
	s_waitcnt vmcnt(0)
	v_pk_mul_f32 v[12:13], v[12:13], v[24:25]
	v_pk_mul_f32 v[24:25], v[62:63], v[2:3] op_sel_hi:[1,0]
	v_cvt_pk_bf16_f32 v12, v12, v13
	v_pk_mul_f32 v[14:15], v[14:15], v[24:25]
	v_pk_mul_f32 v[24:25], v[58:59], v[2:3] op_sel_hi:[1,0]
	v_cvt_pk_bf16_f32 v13, v14, v15
	global_store_dwordx2 v[80:81], v[12:13], off offset:176
	global_load_dwordx4 v[12:15], v119, s[56:57] offset:384
	s_waitcnt vmcnt(0)
	v_pk_mul_f32 v[12:13], v[12:13], v[24:25]
	v_pk_mul_f32 v[24:25], v[56:57], v[2:3] op_sel_hi:[1,0]
	v_cvt_pk_bf16_f32 v12, v12, v13
	v_pk_mul_f32 v[14:15], v[14:15], v[24:25]
	v_pk_mul_f32 v[24:25], v[54:55], v[2:3] op_sel_hi:[1,0]
	v_cvt_pk_bf16_f32 v13, v14, v15
	global_store_dwordx2 v[80:81], v[12:13], off offset:192
	global_load_dwordx4 v[12:15], v119, s[56:57] offset:416
	s_waitcnt vmcnt(0)
	v_pk_mul_f32 v[12:13], v[12:13], v[24:25]
	v_pk_mul_f32 v[24:25], v[52:53], v[2:3] op_sel_hi:[1,0]
	v_cvt_pk_bf16_f32 v12, v12, v13
	v_pk_mul_f32 v[14:15], v[14:15], v[24:25]
	v_pk_mul_f32 v[24:25], v[50:51], v[2:3] op_sel_hi:[1,0]
	v_cvt_pk_bf16_f32 v13, v14, v15
	global_store_dwordx2 v[80:81], v[12:13], off offset:208
	global_load_dwordx4 v[12:15], v119, s[56:57] offset:448
	s_waitcnt vmcnt(0)
	v_pk_mul_f32 v[12:13], v[12:13], v[24:25]
	v_pk_mul_f32 v[24:25], v[48:49], v[2:3] op_sel_hi:[1,0]
	v_cvt_pk_bf16_f32 v12, v12, v13
	v_pk_mul_f32 v[14:15], v[14:15], v[24:25]
	v_pk_mul_f32 v[24:25], v[44:45], v[2:3] op_sel_hi:[1,0]
	v_cvt_pk_bf16_f32 v13, v14, v15
	global_store_dwordx2 v[80:81], v[12:13], off offset:224
	global_load_dwordx4 v[12:15], v119, s[56:57] offset:480
	s_waitcnt vmcnt(0)
	v_pk_mul_f32 v[12:13], v[12:13], v[24:25]
	v_pk_mul_f32 v[24:25], v[46:47], v[2:3] op_sel_hi:[1,0]
	v_cvt_pk_bf16_f32 v12, v12, v13
	v_pk_mul_f32 v[14:15], v[14:15], v[24:25]
	s_nop 0
	v_cvt_pk_bf16_f32 v13, v14, v15
	global_store_dwordx2 v[80:81], v[12:13], off offset:240
	global_load_dword v3, v[40:41], off
	global_load_dwordx4 v[24:27], v119, s[72:73] offset:256
	global_load_dwordx4 v[28:31], v119, s[56:57] offset:512
	s_waitcnt vmcnt(2)
	v_cvt_f32_i32_e32 v3, v3
	s_waitcnt vmcnt(1)
	v_mul_f32_e32 v12, v24, v3
	v_mul_f32_e32 v13, 0.15915494, v12
	v_fma_f32 v14, v12, 0.15915494, -v13
	v_fract_f32_e32 v13, v13
	v_fmac_f32_e32 v14, 0x31dc9c88, v12
	v_add_f32_e32 v13, v13, v14
	v_pk_mul_f32 v[14:15], v[42:43], v[2:3] op_sel_hi:[1,0]
	v_sin_f32_e32 v12, v13
	s_waitcnt vmcnt(0)
	v_pk_mul_f32 v[28:29], v[28:29], v[14:15]
	v_pk_mul_f32 v[14:15], v[38:39], v[2:3] op_sel_hi:[1,0]
	global_load_dwordx4 v[38:41], v119, s[56:57] offset:640
	v_cos_f32_e32 v24, v13
	v_mul_f32_e32 v13, v25, v3
	v_pk_mul_f32 v[18:19], v[18:19], v[2:3] op_sel_hi:[1,0]
	v_pk_mul_f32 v[8:9], v[8:9], v[2:3] op_sel_hi:[1,0]
	v_pk_mul_f32 v[10:11], v[10:11], v[2:3] op_sel_hi:[1,0]
	v_pk_mul_f32 v[6:7], v[6:7], v[2:3] op_sel_hi:[1,0]
	v_pk_mul_f32 v[4:5], v[4:5], v[2:3] op_sel_hi:[1,0]
	v_pk_mul_f32 v[0:1], v[0:1], v[2:3] op_sel_hi:[1,0]
	s_waitcnt vmcnt(0)
; DI unsigned pk2(float a, float b) { f2_t v = {a, b}; bf2_t r = __builtin_convertvector(v, bf2_t); return __builtin_bit_cast(unsigned, r); }
; DI void q_tile(const Params& p, int mt, int hd, unsigned char* smem) {
;     ...
;     for (int g = 0; g < 4; ++g) {
;         float o1[4], o2[4];
; #pragma unroll
;         for (int jj = 0; jj < 4; ++jj) {
;             const int i = 8 * g + 4 * h + jj;
;             float sn, cs; sincos_rev(posf * invf[i], sn, cs);
;             const float x1 = acc[0][4][4 * g + jj] * rs * p.q_gain[128 + i], x2 = acc[0][5][4 * g + jj] * rs * p.q_gain[160 + i];
;             o1[jj] = x1 * cs - x2 * sn; o2[jj] = x2 * cs + x1 * sn;
;         }
;         u32x2 a; a.x = pk2(o1[0], o1[1]); a.y = pk2(o1[2], o1[3]);
;         u32x2 c; c.x = pk2(o2[0], o2[1]); c.y = pk2(o2[2], o2[3]);
;         *(u32x2*)(qrow + 128 + 8 * g + 4 * h) = a;
;         *(u32x2*)(qrow + 160 + 8 * g + 4 * h) = c;
;     }
	v_pk_mul_f32 v[38:39], v[38:39], v[14:15]
	v_mul_f32_e32 v14, 0.15915494, v13
	v_fma_f32 v15, v13, 0.15915494, -v14
	v_fract_f32_e32 v14, v14
	v_fmac_f32_e32 v15, 0x31dc9c88, v13
	v_add_f32_e32 v14, v14, v15
	v_sin_f32_e32 v13, v14
	v_cos_f32_e32 v25, v14
	v_pk_mul_f32 v[14:15], v[12:13], v[38:39]
	s_nop 0
	v_pk_fma_f32 v[14:15], v[24:25], v[28:29], v[14:15] neg_lo:[0,0,1] neg_hi:[0,0,1]
	v_pk_mul_f32 v[24:25], v[24:25], v[38:39]
	v_cvt_pk_bf16_f32 v14, v14, v15
	v_pk_fma_f32 v[12:13], v[12:13], v[28:29], v[24:25]
	v_mul_f32_e32 v24, v26, v3
	v_mul_f32_e32 v25, 0.15915494, v24
	v_fma_f32 v26, v24, 0.15915494, -v25
	v_fract_f32_e32 v25, v25
	v_fmac_f32_e32 v26, 0x31dc9c88, v24
	v_add_f32_e32 v25, v25, v26
	v_sin_f32_e32 v24, v25
	v_cos_f32_e32 v26, v25
	v_mul_f32_e32 v25, v27, v3
	v_pk_mul_f32 v[28:29], v[36:37], v[2:3] op_sel_hi:[1,0]
	v_mul_f32_e32 v27, 0.15915494, v25
	v_pk_mul_f32 v[28:29], v[30:31], v[28:29]
	v_pk_mul_f32 v[30:31], v[34:35], v[2:3] op_sel_hi:[1,0]
	v_fma_f32 v34, v25, 0.15915494, -v27
	v_fract_f32_e32 v27, v27
	v_fmac_f32_e32 v34, 0x31dc9c88, v25
	v_add_f32_e32 v27, v27, v34
	v_sin_f32_e32 v25, v27
	v_cos_f32_e32 v27, v27
	v_pk_mul_f32 v[30:31], v[40:41], v[30:31]
	v_cvt_pk_bf16_f32 v12, v12, v13
	v_pk_mul_f32 v[34:35], v[24:25], v[30:31]
	s_nop 0
	v_pk_fma_f32 v[34:35], v[26:27], v[28:29], v[34:35] neg_lo:[0,0,1] neg_hi:[0,0,1]
	v_pk_mul_f32 v[26:27], v[26:27], v[30:31]
	v_cvt_pk_bf16_f32 v15, v34, v35
	v_pk_fma_f32 v[24:25], v[24:25], v[28:29], v[26:27]
	s_nop 0
	v_cvt_pk_bf16_f32 v13, v24, v25
	global_store_dwordx2 v[80:81], v[14:15], off offset:256
	global_store_dwordx2 v[80:81], v[12:13], off offset:320
	global_load_dwordx4 v[24:27], v119, s[72:73] offset:288
	global_load_dwordx4 v[28:31], v119, s[56:57] offset:544
	s_waitcnt vmcnt(1)
	v_mul_f32_e32 v12, v24, v3
	v_mul_f32_e32 v13, 0.15915494, v12
	v_fma_f32 v14, v12, 0.15915494, -v13
	v_fract_f32_e32 v13, v13
	v_fmac_f32_e32 v14, 0x31dc9c88, v12
	v_add_f32_e32 v13, v13, v14
	v_pk_mul_f32 v[14:15], v[22:23], v[2:3] op_sel_hi:[1,0]
	v_sin_f32_e32 v12, v13
	s_waitcnt vmcnt(0)
	v_pk_mul_f32 v[28:29], v[28:29], v[14:15]
	v_pk_mul_f32 v[14:15], v[20:21], v[2:3] op_sel_hi:[1,0]
	global_load_dwordx4 v[20:23], v119, s[56:57] offset:672
	v_cos_f32_e32 v24, v13
	v_mul_f32_e32 v13, v25, v3
	s_waitcnt vmcnt(0)
	v_pk_mul_f32 v[20:21], v[20:21], v[14:15]
	v_mul_f32_e32 v14, 0.15915494, v13
	v_fma_f32 v15, v13, 0.15915494, -v14
	v_fract_f32_e32 v14, v14
	v_fmac_f32_e32 v15, 0x31dc9c88, v13
	v_add_f32_e32 v14, v14, v15
	v_sin_f32_e32 v13, v14
	v_cos_f32_e32 v25, v14
	v_pk_mul_f32 v[18:19], v[22:23], v[18:19]
	v_pk_mul_f32 v[14:15], v[12:13], v[20:21]
	v_pk_mul_f32 v[20:21], v[24:25], v[20:21]
	v_pk_fma_f32 v[14:15], v[24:25], v[28:29], v[14:15] neg_lo:[0,0,1] neg_hi:[0,0,1]
	v_pk_fma_f32 v[12:13], v[12:13], v[28:29], v[20:21]
	v_mul_f32_e32 v20, v26, v3
	v_mul_f32_e32 v21, 0.15915494, v20
	v_fma_f32 v24, v20, 0.15915494, -v21
	v_fract_f32_e32 v21, v21
	v_fmac_f32_e32 v24, 0x31dc9c88, v20
	v_add_f32_e32 v21, v21, v24
	v_sin_f32_e32 v20, v21
	v_cos_f32_e32 v24, v21
	v_mul_f32_e32 v21, v27, v3
	v_mul_f32_e32 v22, 0.15915494, v21
	v_fma_f32 v23, v21, 0.15915494, -v22
	v_fract_f32_e32 v22, v22
	v_fmac_f32_e32 v23, 0x31dc9c88, v21
	v_add_f32_e32 v22, v22, v23
	v_sin_f32_e32 v21, v22
	v_cos_f32_e32 v25, v22
	v_pk_mul_f32 v[28:29], v[32:33], v[2:3] op_sel_hi:[1,0]
	v_cvt_pk_bf16_f32 v14, v14, v15
	v_pk_mul_f32 v[28:29], v[30:31], v[28:29]
	v_pk_mul_f32 v[22:23], v[20:21], v[18:19]
	v_pk_mul_f32 v[18:19], v[24:25], v[18:19]
	v_pk_fma_f32 v[22:23], v[24:25], v[28:29], v[22:23] neg_lo:[0,0,1] neg_hi:[0,0,1]
	v_pk_fma_f32 v[18:19], v[20:21], v[28:29], v[18:19]
	v_cvt_pk_bf16_f32 v15, v22, v23
	v_cvt_pk_bf16_f32 v12, v12, v13
	v_cvt_pk_bf16_f32 v13, v18, v19
	global_store_dwordx2 v[80:81], v[14:15], off offset:272
	global_store_dwordx2 v[80:81], v[12:13], off offset:336
	global_load_dwordx4 v[12:15], v119, s[72:73] offset:320
	v_pk_mul_f32 v[20:21], v[16:17], v[2:3] op_sel_hi:[1,0]
	s_waitcnt vmcnt(0)
; DI unsigned pk2(float a, float b) { f2_t v = {a, b}; bf2_t r = __builtin_convertvector(v, bf2_t); return __builtin_bit_cast(unsigned, r); }
; DI void q_tile(const Params& p, int mt, int hd, unsigned char* smem) {
;     ...
;     for (int g = 0; g < 4; ++g) {
;         float o1[4], o2[4];
; #pragma unroll
;         for (int jj = 0; jj < 4; ++jj) {
;             const int i = 8 * g + 4 * h + jj;
;             float sn, cs; sincos_rev(posf * invf[i], sn, cs);
;             const float x1 = acc[0][4][4 * g + jj] * rs * p.q_gain[128 + i], x2 = acc[0][5][4 * g + jj] * rs * p.q_gain[160 + i];
;             o1[jj] = x1 * cs - x2 * sn; o2[jj] = x2 * cs + x1 * sn;
;         }
;         u32x2 a; a.x = pk2(o1[0], o1[1]); a.y = pk2(o1[2], o1[3]);
;         u32x2 c; c.x = pk2(o2[0], o2[1]); c.y = pk2(o2[2], o2[3]);
;         *(u32x2*)(qrow + 128 + 8 * g + 4 * h) = a;
;         *(u32x2*)(qrow + 160 + 8 * g + 4 * h) = c;
;     }
	v_mul_f32_e32 v12, v12, v3
	v_mul_f32_e32 v18, 0.15915494, v12
	v_fma_f32 v19, v12, 0.15915494, -v18
	v_fract_f32_e32 v18, v18
	v_fmac_f32_e32 v19, 0x31dc9c88, v12
	v_add_f32_e32 v12, v18, v19
	global_load_dwordx4 v[16:19], v119, s[56:57] offset:576
	v_sin_f32_e32 v24, v12
	v_cos_f32_e32 v26, v12
	v_mul_f32_e32 v12, v13, v3
	v_mul_f32_e32 v13, 0.15915494, v12
	v_mul_f32_e32 v14, v14, v3
	v_mul_f32_e32 v15, v15, v3
	s_waitcnt vmcnt(0)
	v_pk_mul_f32 v[16:17], v[16:17], v[20:21]
	global_load_dwordx4 v[20:23], v119, s[56:57] offset:704
	v_pk_mul_f32 v[10:11], v[18:19], v[10:11]
	s_waitcnt vmcnt(0)
	v_pk_mul_f32 v[8:9], v[20:21], v[8:9]
	v_fma_f32 v20, v12, 0.15915494, -v13
	v_fract_f32_e32 v13, v13
	v_fmac_f32_e32 v20, 0x31dc9c88, v12
	v_add_f32_e32 v12, v13, v20
	v_sin_f32_e32 v25, v12
	v_cos_f32_e32 v27, v12
	v_pk_mul_f32 v[6:7], v[22:23], v[6:7]
	v_pk_mul_f32 v[12:13], v[24:25], v[8:9]
	v_pk_mul_f32 v[8:9], v[26:27], v[8:9]
	v_pk_fma_f32 v[12:13], v[26:27], v[16:17], v[12:13] neg_lo:[0,0,1] neg_hi:[0,0,1]
	v_pk_fma_f32 v[8:9], v[24:25], v[16:17], v[8:9]
	v_mul_f32_e32 v16, 0.15915494, v14
	v_fma_f32 v17, v14, 0.15915494, -v16
	v_fract_f32_e32 v16, v16
	v_fmac_f32_e32 v17, 0x31dc9c88, v14
	v_add_f32_e32 v16, v16, v17
	v_mul_f32_e32 v17, 0.15915494, v15
	v_fma_f32 v18, v15, 0.15915494, -v17
	v_fract_f32_e32 v17, v17
	v_fmac_f32_e32 v18, 0x31dc9c88, v15
	v_add_f32_e32 v17, v17, v18
	v_sin_f32_e32 v14, v16
	v_sin_f32_e32 v15, v17
	v_cos_f32_e32 v16, v16
	v_cos_f32_e32 v17, v17
	v_cvt_pk_bf16_f32 v8, v8, v9
	v_pk_mul_f32 v[18:19], v[14:15], v[6:7]
	v_pk_mul_f32 v[6:7], v[16:17], v[6:7]
	v_pk_fma_f32 v[18:19], v[16:17], v[10:11], v[18:19] neg_lo:[0,0,1] neg_hi:[0,0,1]
	v_pk_fma_f32 v[6:7], v[14:15], v[10:11], v[6:7]
	v_cvt_pk_bf16_f32 v10, v12, v13
	v_cvt_pk_bf16_f32 v11, v18, v19
	v_cvt_pk_bf16_f32 v9, v6, v7
	global_store_dwordx2 v[80:81], v[10:11], off offset:288
	global_store_dwordx2 v[80:81], v[8:9], off offset:352
	global_load_dwordx4 v[6:9], v119, s[72:73] offset:352
	s_waitcnt vmcnt(0)
	v_mul_f32_e32 v6, v6, v3
	v_mul_f32_e32 v10, 0.15915494, v6
	v_fma_f32 v11, v6, 0.15915494, -v10
	v_fract_f32_e32 v10, v10
	v_fmac_f32_e32 v11, 0x31dc9c88, v6
	v_add_f32_e32 v6, v10, v11
	global_load_dwordx4 v[10:13], v119, s[56:57] offset:608
	global_load_dwordx4 v[14:17], v119, s[56:57] offset:736
	v_sin_f32_e32 v18, v6
	v_cos_f32_e32 v20, v6
	v_mul_f32_e32 v6, v7, v3
	v_mul_f32_e32 v7, 0.15915494, v6
	v_mul_f32_e32 v8, v8, v3
	s_waitcnt vmcnt(1)
	v_pk_mul_f32 v[4:5], v[10:11], v[4:5]
	v_pk_mul_f32 v[10:11], v[98:99], v[2:3] op_sel_hi:[1,0]
	v_pk_mul_f32 v[0:1], v[12:13], v[0:1]
	s_waitcnt vmcnt(0)
	v_pk_mul_f32 v[10:11], v[14:15], v[10:11]
	v_fma_f32 v14, v6, 0.15915494, -v7
	v_fract_f32_e32 v7, v7
	v_fmac_f32_e32 v14, 0x31dc9c88, v6
	v_add_f32_e32 v6, v7, v14
	v_sin_f32_e32 v19, v6
	v_cos_f32_e32 v21, v6
	v_pk_mul_f32 v[12:13], v[96:97], v[2:3] op_sel_hi:[1,0]
	v_mul_f32_e32 v2, v9, v3
	v_pk_mul_f32 v[6:7], v[18:19], v[10:11]
	v_pk_mul_f32 v[10:11], v[20:21], v[10:11]
	v_pk_fma_f32 v[6:7], v[20:21], v[4:5], v[6:7] neg_lo:[0,0,1] neg_hi:[0,0,1]
	v_pk_fma_f32 v[4:5], v[18:19], v[4:5], v[10:11]
	v_mul_f32_e32 v10, 0.15915494, v8
	v_mul_f32_e32 v3, 0.15915494, v2
	v_fma_f32 v11, v8, 0.15915494, -v10
	v_fma_f32 v9, v2, 0.15915494, -v3
	v_fract_f32_e32 v10, v10
	v_fmac_f32_e32 v11, 0x31dc9c88, v8
	v_fract_f32_e32 v3, v3
	v_fmac_f32_e32 v9, 0x31dc9c88, v2
	v_add_f32_e32 v10, v10, v11
	v_add_f32_e32 v2, v3, v9
	v_sin_f32_e32 v8, v10
	v_sin_f32_e32 v9, v2
	v_cos_f32_e32 v10, v10
	v_cos_f32_e32 v11, v2
	v_pk_mul_f32 v[12:13], v[16:17], v[12:13]
	v_cvt_pk_bf16_f32 v6, v6, v7
	v_pk_mul_f32 v[2:3], v[8:9], v[12:13]
	s_nop 0
	v_pk_fma_f32 v[2:3], v[10:11], v[0:1], v[2:3] neg_lo:[0,0,1] neg_hi:[0,0,1]
	v_pk_mul_f32 v[10:11], v[10:11], v[12:13]
	v_cvt_pk_bf16_f32 v7, v2, v3
	v_pk_fma_f32 v[0:1], v[8:9], v[0:1], v[10:11]
	v_cvt_pk_bf16_f32 v2, v4, v5
	v_cvt_pk_bf16_f32 v3, v0, v1
	global_store_dwordx2 v[80:81], v[6:7], off offset:304
	global_store_dwordx2 v[80:81], v[2:3], off offset:368

; #define G3_LDA(buf, kt, i) __builtin_amdgcn_global_load_lds((const unsigned*)(ga + (size_t)((i) * 64) * lda + (kt) * 64), (lds_u32*)(sdst + (buf) * STAGE + (i) * 8192), 16, 0, 0)
; #define G3_LDB(buf, kt, i) __builtin_amdgcn_global_load_lds((const unsigned*)(gb + (size_t)((i) * 64) * ldb + (kt) * 64), (lds_u32*)(sdst + (buf) * STAGE + B_OFF + (i) * 8192), 16, 0, 0)
; DI void gemm3_mainloop(const int wave8, const int lane, const bf16_t* __restrict__ A, int lda, const bf16_t* __restrict__ Bt, int ldb, int K,
;                        unsigned char* smem, f32x4 (&acc)[8][4]) {
;     ...
;     asm volatile("s_waitcnt vmcnt(0)" ::: "memory");
;     G3_LDA(0, 0, 0); G3_LDA(0, 0, 1); G3_LDA(0, 0, 2); G3_LDA(0, 0, 3); G3_LDB(0, 0, 0); G3_LDB(0, 0, 1); G3_LDB(0, 0, 2); G3_LDB(0, 0, 3);
;     asm volatile("s_waitcnt vmcnt(0)" ::: "memory");
;     __builtin_amdgcn_s_barrier();
;     for (int kt = 0; kt < nk; kt += 2) { G3_STEP(0, 1, kt); G3_STEP(1, 0, kt + 1); }
.LBB0_503:
	ds_read_b128 v[148:151], v139 offset:32768
	ds_read_b128 v[164:167], v140
	ds_read_b128 v[152:155], v139 offset:34816
	ds_read_b128 v[156:159], v139 offset:36864
	ds_read_b128 v[160:163], v139 offset:38912
	ds_read_b128 v[168:171], v140 offset:2048
	ds_read_b128 v[172:175], v140 offset:4096
	ds_read_b128 v[176:179], v140 offset:6144
	ds_read_b128 v[180:183], v140 offset:8192
	ds_read_b128 v[184:187], v140 offset:10240
	ds_read_b128 v[188:191], v140 offset:12288
	ds_read_b128 v[192:195], v140 offset:14336
	v_lshl_add_u64 v[196:197], v[134:135], 0, v[128:129]
	s_mov_b32 m0, s88
	s_waitcnt lgkmcnt(10)
	v_mfma_f32_16x16x32_bf16 v[124:127], v[148:151], v[164:167], v[124:127]
	s_add_i32 s50, s2, 1
	s_add_i32 s47, s2, 2
	s_cmp_lt_u32 s2, 30
	s_waitcnt lgkmcnt(9)
	v_mfma_f32_16x16x32_bf16 v[120:123], v[152:155], v[164:167], v[120:123]
	s_cselect_b64 s[48:49], -1, 0
	s_and_b64 vcc, s[48:49], exec
	s_cselect_b32 s2, s47, s50
	s_waitcnt lgkmcnt(8)
	v_mfma_f32_16x16x32_bf16 v[116:119], v[156:159], v[164:167], v[116:119]
	s_lshl_b32 s2, s2, 7
	v_lshl_add_u64 v[134:135], v[134:135], 0, s[26:27]
	s_waitcnt lgkmcnt(7)
	v_mfma_f32_16x16x32_bf16 v[112:115], v[160:163], v[164:167], v[112:115]
	v_lshl_add_u64 v[164:165], v[196:197], 0, s[10:11]
	global_load_lds_dwordx4 v[164:165], off
	v_lshl_add_u64 v[164:165], v[196:197], 0, s[12:13]
	s_mov_b32 m0, s92
	s_waitcnt lgkmcnt(6)
	v_mfma_f32_16x16x32_bf16 v[108:111], v[148:151], v[168:171], v[108:111]
	v_mfma_f32_16x16x32_bf16 v[104:107], v[152:155], v[168:171], v[104:107]
	v_mfma_f32_16x16x32_bf16 v[100:103], v[156:159], v[168:171], v[100:103]
	v_mfma_f32_16x16x32_bf16 v[96:99], v[160:163], v[168:171], v[96:99]
	global_load_lds_dwordx4 v[164:165], off
	v_lshl_add_u64 v[164:165], v[196:197], 0, s[14:15]
	s_mov_b32 m0, s93
	s_waitcnt lgkmcnt(5)
	v_mfma_f32_16x16x32_bf16 v[92:95], v[148:151], v[172:175], v[92:95]
	v_mfma_f32_16x16x32_bf16 v[88:91], v[152:155], v[172:175], v[88:91]
	v_mfma_f32_16x16x32_bf16 v[84:87], v[156:159], v[172:175], v[84:87]
	v_mfma_f32_16x16x32_bf16 v[80:83], v[160:163], v[172:175], v[80:83]
	global_load_lds_dwordx4 v[164:165], off
	v_lshl_add_u64 v[164:165], v[196:197], 0, s[16:17]
	s_mov_b32 m0, s94
	s_waitcnt lgkmcnt(4)
	v_mfma_f32_16x16x32_bf16 v[76:79], v[148:151], v[176:179], v[76:79]
	v_lshl_add_u64 v[196:197], v[136:137], 0, v[128:129]
	v_lshl_add_u64 v[198:199], v[196:197], 0, s[18:19]
	v_lshl_add_u64 v[136:137], v[136:137], 0, s[26:27]
	v_mfma_f32_16x16x32_bf16 v[72:75], v[152:155], v[176:179], v[72:75]
	v_mfma_f32_16x16x32_bf16 v[68:71], v[156:159], v[176:179], v[68:71]
	v_mfma_f32_16x16x32_bf16 v[64:67], v[160:163], v[176:179], v[64:67]
	global_load_lds_dwordx4 v[164:165], off
	s_mov_b32 m0, s89
	s_waitcnt lgkmcnt(3)
	v_mfma_f32_16x16x32_bf16 v[60:63], v[148:151], v[180:183], v[60:63]
	v_mfma_f32_16x16x32_bf16 v[56:59], v[152:155], v[180:183], v[56:59]
	v_mfma_f32_16x16x32_bf16 v[52:55], v[156:159], v[180:183], v[52:55]
	v_mfma_f32_16x16x32_bf16 v[48:51], v[160:163], v[180:183], v[48:51]
	s_waitcnt lgkmcnt(2)
	v_mfma_f32_16x16x32_bf16 v[44:47], v[148:151], v[184:187], v[44:47]
	v_mfma_f32_16x16x32_bf16 v[40:43], v[152:155], v[184:187], v[40:43]
	v_mfma_f32_16x16x32_bf16 v[36:39], v[156:159], v[184:187], v[36:39]
	v_mfma_f32_16x16x32_bf16 v[28:31], v[160:163], v[184:187], v[28:31]
	s_waitcnt lgkmcnt(1)
	v_mfma_f32_16x16x32_bf16 v[24:27], v[148:151], v[188:191], v[24:27]
	v_mfma_f32_16x16x32_bf16 v[20:23], v[152:155], v[188:191], v[20:23]
	v_mfma_f32_16x16x32_bf16 v[16:19], v[156:159], v[188:191], v[16:19]
	v_mfma_f32_16x16x32_bf16 v[12:15], v[160:163], v[188:191], v[12:15]
	s_waitcnt lgkmcnt(0)
	v_mfma_f32_16x16x32_bf16 v[8:11], v[148:151], v[192:195], v[8:11]
	v_mfma_f32_16x16x32_bf16 v[4:7], v[152:155], v[192:195], v[4:7]
	v_mfma_f32_16x16x32_bf16 v[0:3], v[156:159], v[192:195], v[0:3]
	v_mfma_f32_16x16x32_bf16 v[32:35], v[160:163], v[192:195], v[32:35]
	ds_read_b128 v[148:151], v141 offset:32768
	ds_read_b128 v[164:167], v142
	ds_read_b128 v[152:155], v141 offset:34816
	ds_read_b128 v[156:159], v141 offset:36864
	ds_read_b128 v[160:163], v141 offset:38912
	ds_read_b128 v[168:171], v142 offset:2048
	ds_read_b128 v[172:175], v142 offset:4096
	ds_read_b128 v[176:179], v142 offset:6144
	ds_read_b128 v[180:183], v142 offset:8192
	ds_read_b128 v[184:187], v142 offset:10240
	ds_read_b128 v[188:191], v142 offset:12288
	ds_read_b128 v[192:195], v142 offset:14336
	s_waitcnt lgkmcnt(10)
	v_mfma_f32_16x16x32_bf16 v[124:127], v[148:151], v[164:167], v[124:127]
	s_waitcnt lgkmcnt(9)
	v_mfma_f32_16x16x32_bf16 v[120:123], v[152:155], v[164:167], v[120:123]
	s_waitcnt lgkmcnt(8)
	v_mfma_f32_16x16x32_bf16 v[116:119], v[156:159], v[164:167], v[116:119]
	s_waitcnt lgkmcnt(7)
	v_mfma_f32_16x16x32_bf16 v[112:115], v[160:163], v[164:167], v[112:115]
	global_load_lds_dwordx4 v[198:199], off
	v_lshl_add_u64 v[164:165], v[196:197], 0, s[20:21]
	s_mov_b32 m0, s95
	s_waitcnt lgkmcnt(6)
	v_mfma_f32_16x16x32_bf16 v[108:111], v[148:151], v[168:171], v[108:111]
	v_mfma_f32_16x16x32_bf16 v[104:107], v[152:155], v[168:171], v[104:107]
	v_mfma_f32_16x16x32_bf16 v[100:103], v[156:159], v[168:171], v[100:103]
	v_mfma_f32_16x16x32_bf16 v[96:99], v[160:163], v[168:171], v[96:99]
	global_load_lds_dwordx4 v[164:165], off
	v_lshl_add_u64 v[164:165], v[196:197], 0, s[22:23]
	s_mov_b32 m0, s96
	s_waitcnt lgkmcnt(5)
	v_mfma_f32_16x16x32_bf16 v[92:95], v[148:151], v[172:175], v[92:95]
	v_mfma_f32_16x16x32_bf16 v[88:91], v[152:155], v[172:175], v[88:91]
	v_mfma_f32_16x16x32_bf16 v[84:87], v[156:159], v[172:175], v[84:87]
	v_mfma_f32_16x16x32_bf16 v[80:83], v[160:163], v[172:175], v[80:83]
	global_load_lds_dwordx4 v[164:165], off
	v_lshl_add_u64 v[164:165], v[196:197], 0, s[24:25]
	s_mov_b32 m0, s97
	s_waitcnt lgkmcnt(4)
; #define G3_LDA(buf, kt, i) __builtin_amdgcn_global_load_lds((const unsigned*)(ga + (size_t)((i) * 64) * lda + (kt) * 64), (lds_u32*)(sdst + (buf) * STAGE + (i) * 8192), 16, 0, 0)
; #define G3_LDB(buf, kt, i) __builtin_amdgcn_global_load_lds((const unsigned*)(gb + (size_t)((i) * 64) * ldb + (kt) * 64), (lds_u32*)(sdst + (buf) * STAGE + B_OFF + (i) * 8192), 16, 0, 0)
; DI void gemm3_mainloop(const int wave8, const int lane, const bf16_t* __restrict__ A, int lda, const bf16_t* __restrict__ Bt, int ldb, int K,
;                        unsigned char* smem, f32x4 (&acc)[8][4]) {
;     ...
;     asm volatile("s_waitcnt vmcnt(0)" ::: "memory");
;     G3_LDA(0, 0, 0); G3_LDA(0, 0, 1); G3_LDA(0, 0, 2); G3_LDA(0, 0, 3); G3_LDB(0, 0, 0); G3_LDB(0, 0, 1); G3_LDB(0, 0, 2); G3_LDB(0, 0, 3);
;     asm volatile("s_waitcnt vmcnt(0)" ::: "memory");
;     __builtin_amdgcn_s_barrier();
;     for (int kt = 0; kt < nk; kt += 2) { G3_STEP(0, 1, kt); G3_STEP(1, 0, kt + 1); }
	v_mfma_f32_16x16x32_bf16 v[76:79], v[148:151], v[176:179], v[76:79]
	v_lshl_add_u64 v[196:197], v[130:131], 0, s[2:3]
	v_mfma_f32_16x16x32_bf16 v[72:75], v[152:155], v[176:179], v[72:75]
	v_mfma_f32_16x16x32_bf16 v[68:71], v[156:159], v[176:179], v[68:71]
	v_mfma_f32_16x16x32_bf16 v[64:67], v[160:163], v[176:179], v[64:67]
	global_load_lds_dwordx4 v[164:165], off
	s_waitcnt lgkmcnt(3)
	v_mfma_f32_16x16x32_bf16 v[60:63], v[148:151], v[180:183], v[60:63]
	s_mov_b32 m0, s0
	v_mfma_f32_16x16x32_bf16 v[56:59], v[152:155], v[180:183], v[56:59]
	v_mfma_f32_16x16x32_bf16 v[52:55], v[156:159], v[180:183], v[52:55]
	v_mfma_f32_16x16x32_bf16 v[48:51], v[160:163], v[180:183], v[48:51]
	s_waitcnt lgkmcnt(2)
	v_mfma_f32_16x16x32_bf16 v[44:47], v[148:151], v[184:187], v[44:47]
	v_mfma_f32_16x16x32_bf16 v[40:43], v[152:155], v[184:187], v[40:43]
	v_mfma_f32_16x16x32_bf16 v[36:39], v[156:159], v[184:187], v[36:39]
	v_mfma_f32_16x16x32_bf16 v[28:31], v[160:163], v[184:187], v[28:31]
	s_waitcnt lgkmcnt(1)
	v_mfma_f32_16x16x32_bf16 v[24:27], v[148:151], v[188:191], v[24:27]
	v_mfma_f32_16x16x32_bf16 v[20:23], v[152:155], v[188:191], v[20:23]
	v_mfma_f32_16x16x32_bf16 v[16:19], v[156:159], v[188:191], v[16:19]
	v_mfma_f32_16x16x32_bf16 v[12:15], v[160:163], v[188:191], v[12:15]
	s_waitcnt vmcnt(0)
	s_barrier
	s_waitcnt lgkmcnt(0)
	v_mfma_f32_16x16x32_bf16 v[8:11], v[148:151], v[192:195], v[8:11]
	v_mfma_f32_16x16x32_bf16 v[4:7], v[152:155], v[192:195], v[4:7]
	v_mfma_f32_16x16x32_bf16 v[0:3], v[156:159], v[192:195], v[0:3]
	v_mfma_f32_16x16x32_bf16 v[32:35], v[160:163], v[192:195], v[32:35]
	ds_read_b128 v[148:151], v143
	ds_read_b128 v[164:167], v144
	ds_read_b128 v[152:155], v143 offset:2048
	ds_read_b128 v[156:159], v143 offset:4096
	ds_read_b128 v[160:163], v143 offset:6144
	ds_read_b128 v[168:171], v144 offset:2048
	ds_read_b128 v[172:175], v144 offset:4096
	ds_read_b128 v[176:179], v144 offset:6144
	ds_read_b128 v[180:183], v144 offset:8192
	ds_read_b128 v[184:187], v144 offset:10240
	ds_read_b128 v[188:191], v144 offset:12288
	ds_read_b128 v[192:195], v144 offset:14336
	s_waitcnt lgkmcnt(10)
	v_mfma_f32_16x16x32_bf16 v[124:127], v[148:151], v[164:167], v[124:127]
	s_waitcnt lgkmcnt(9)
	v_mfma_f32_16x16x32_bf16 v[120:123], v[152:155], v[164:167], v[120:123]
	s_waitcnt lgkmcnt(8)
	v_mfma_f32_16x16x32_bf16 v[116:119], v[156:159], v[164:167], v[116:119]
	s_waitcnt lgkmcnt(7)
	v_mfma_f32_16x16x32_bf16 v[112:115], v[160:163], v[164:167], v[112:115]
	global_load_lds_dwordx4 v[196:197], off
	v_lshl_add_u64 v[164:165], v[196:197], 0, s[4:5]
	s_mov_b32 m0, s55
	s_waitcnt lgkmcnt(6)
	v_mfma_f32_16x16x32_bf16 v[108:111], v[148:151], v[168:171], v[108:111]
	v_mfma_f32_16x16x32_bf16 v[104:107], v[152:155], v[168:171], v[104:107]
	v_mfma_f32_16x16x32_bf16 v[100:103], v[156:159], v[168:171], v[100:103]
	v_mfma_f32_16x16x32_bf16 v[96:99], v[160:163], v[168:171], v[96:99]
	global_load_lds_dwordx4 v[164:165], off
	v_lshl_add_u64 v[164:165], v[196:197], 0, s[6:7]
	s_mov_b32 m0, s87
	s_waitcnt lgkmcnt(5)
	v_mfma_f32_16x16x32_bf16 v[92:95], v[148:151], v[172:175], v[92:95]
	v_mfma_f32_16x16x32_bf16 v[88:91], v[152:155], v[172:175], v[88:91]
	v_mfma_f32_16x16x32_bf16 v[84:87], v[156:159], v[172:175], v[84:87]
	v_mfma_f32_16x16x32_bf16 v[80:83], v[160:163], v[172:175], v[80:83]
	global_load_lds_dwordx4 v[164:165], off
	v_lshl_add_u64 v[164:165], v[196:197], 0, s[8:9]
	s_mov_b32 m0, s69
	s_waitcnt lgkmcnt(4)
	v_mfma_f32_16x16x32_bf16 v[76:79], v[148:151], v[176:179], v[76:79]
	v_lshl_add_u64 v[196:197], v[132:133], 0, s[2:3]
	s_mov_b32 s2, s47
	v_mfma_f32_16x16x32_bf16 v[72:75], v[152:155], v[176:179], v[72:75]
	v_mfma_f32_16x16x32_bf16 v[68:71], v[156:159], v[176:179], v[68:71]
	v_mfma_f32_16x16x32_bf16 v[64:67], v[160:163], v[176:179], v[64:67]
	global_load_lds_dwordx4 v[164:165], off
	s_mov_b32 m0, s68
	s_waitcnt lgkmcnt(3)
	v_mfma_f32_16x16x32_bf16 v[60:63], v[148:151], v[180:183], v[60:63]
	v_mfma_f32_16x16x32_bf16 v[56:59], v[152:155], v[180:183], v[56:59]
	v_mfma_f32_16x16x32_bf16 v[52:55], v[156:159], v[180:183], v[52:55]
	v_mfma_f32_16x16x32_bf16 v[48:51], v[160:163], v[180:183], v[48:51]
	s_waitcnt lgkmcnt(2)
	v_mfma_f32_16x16x32_bf16 v[44:47], v[148:151], v[184:187], v[44:47]
	v_mfma_f32_16x16x32_bf16 v[40:43], v[152:155], v[184:187], v[40:43]
	v_mfma_f32_16x16x32_bf16 v[36:39], v[156:159], v[184:187], v[36:39]
	v_mfma_f32_16x16x32_bf16 v[28:31], v[160:163], v[184:187], v[28:31]
	s_waitcnt lgkmcnt(1)
	v_mfma_f32_16x16x32_bf16 v[24:27], v[148:151], v[188:191], v[24:27]
	v_mfma_f32_16x16x32_bf16 v[20:23], v[152:155], v[188:191], v[20:23]
	v_mfma_f32_16x16x32_bf16 v[16:19], v[156:159], v[188:191], v[16:19]
	v_mfma_f32_16x16x32_bf16 v[12:15], v[160:163], v[188:191], v[12:15]
	s_waitcnt lgkmcnt(0)
	v_mfma_f32_16x16x32_bf16 v[8:11], v[148:151], v[192:195], v[8:11]
	v_mfma_f32_16x16x32_bf16 v[4:7], v[152:155], v[192:195], v[4:7]
	v_mfma_f32_16x16x32_bf16 v[0:3], v[156:159], v[192:195], v[0:3]
	v_mfma_f32_16x16x32_bf16 v[32:35], v[160:163], v[192:195], v[32:35]
	ds_read_b128 v[148:151], v145
	ds_read_b128 v[164:167], v146
	ds_read_b128 v[152:155], v145 offset:2048
	ds_read_b128 v[156:159], v145 offset:4096
	ds_read_b128 v[160:163], v145 offset:6144
	ds_read_b128 v[168:171], v146 offset:2048
	ds_read_b128 v[172:175], v146 offset:4096
	ds_read_b128 v[176:179], v146 offset:6144
	ds_read_b128 v[180:183], v146 offset:8192
	ds_read_b128 v[184:187], v146 offset:10240
	ds_read_b128 v[188:191], v146 offset:12288
	ds_read_b128 v[192:195], v146 offset:14336
	s_waitcnt lgkmcnt(10)
	v_mfma_f32_16x16x32_bf16 v[124:127], v[148:151], v[164:167], v[124:127]
	s_waitcnt lgkmcnt(9)
; #define G3_LDA(buf, kt, i) __builtin_amdgcn_global_load_lds((const unsigned*)(ga + (size_t)((i) * 64) * lda + (kt) * 64), (lds_u32*)(sdst + (buf) * STAGE + (i) * 8192), 16, 0, 0)
; #define G3_LDB(buf, kt, i) __builtin_amdgcn_global_load_lds((const unsigned*)(gb + (size_t)((i) * 64) * ldb + (kt) * 64), (lds_u32*)(sdst + (buf) * STAGE + B_OFF + (i) * 8192), 16, 0, 0)
; DI void gemm3_mainloop(const int wave8, const int lane, const bf16_t* __restrict__ A, int lda, const bf16_t* __restrict__ Bt, int ldb, int K,
;                        unsigned char* smem, f32x4 (&acc)[8][4]) {
;     ...
;     asm volatile("s_waitcnt vmcnt(0)" ::: "memory");
;     G3_LDA(0, 0, 0); G3_LDA(0, 0, 1); G3_LDA(0, 0, 2); G3_LDA(0, 0, 3); G3_LDB(0, 0, 0); G3_LDB(0, 0, 1); G3_LDB(0, 0, 2); G3_LDB(0, 0, 3);
;     asm volatile("s_waitcnt vmcnt(0)" ::: "memory");
;     __builtin_amdgcn_s_barrier();
;     for (int kt = 0; kt < nk; kt += 2) { G3_STEP(0, 1, kt); G3_STEP(1, 0, kt + 1); }
; DI void phase4(const Params& p, unsigned char* smem) {
;     ...
; #pragma unroll
;         for (int i = 0; i < 8; ++i) {
;             const size_t m = (size_t)mt * 256 + wm * 128 + i * 16 + fr;
; #pragma unroll
;             for (int j = 0; j < 4; ++j) {
;                 const int c = nt * 256 + wn * 64 + j * 16 + fq * 4;
;                 const f32x4 xv = *(const f32x4*)(p.x + m * DM + c);
;                 *(f32x4*)(p.out + m * DM + c) = xv + acc[i][j];
;             }
;         }
	v_mfma_f32_16x16x32_bf16 v[120:123], v[152:155], v[164:167], v[120:123]
	s_waitcnt lgkmcnt(8)
	v_mfma_f32_16x16x32_bf16 v[116:119], v[156:159], v[164:167], v[116:119]
	s_waitcnt lgkmcnt(7)
	v_mfma_f32_16x16x32_bf16 v[112:115], v[160:163], v[164:167], v[112:115]
	global_load_lds_dwordx4 v[196:197], off
	v_lshl_add_u64 v[164:165], v[196:197], 0, s[4:5]
	s_mov_b32 m0, s39
	s_waitcnt lgkmcnt(6)
	v_mfma_f32_16x16x32_bf16 v[108:111], v[148:151], v[168:171], v[108:111]
	v_mfma_f32_16x16x32_bf16 v[104:107], v[152:155], v[168:171], v[104:107]
	v_mfma_f32_16x16x32_bf16 v[100:103], v[156:159], v[168:171], v[100:103]
	v_mfma_f32_16x16x32_bf16 v[96:99], v[160:163], v[168:171], v[96:99]
	global_load_lds_dwordx4 v[164:165], off
	v_lshl_add_u64 v[164:165], v[196:197], 0, s[6:7]
	s_mov_b32 m0, s38
	s_waitcnt lgkmcnt(5)
	v_mfma_f32_16x16x32_bf16 v[92:95], v[148:151], v[172:175], v[92:95]
	v_mfma_f32_16x16x32_bf16 v[88:91], v[152:155], v[172:175], v[88:91]
	v_mfma_f32_16x16x32_bf16 v[84:87], v[156:159], v[172:175], v[84:87]
	v_mfma_f32_16x16x32_bf16 v[80:83], v[160:163], v[172:175], v[80:83]
	global_load_lds_dwordx4 v[164:165], off
	v_lshl_add_u64 v[164:165], v[196:197], 0, s[8:9]
	s_mov_b32 m0, s1
	s_waitcnt lgkmcnt(4)
	v_mfma_f32_16x16x32_bf16 v[76:79], v[148:151], v[176:179], v[76:79]
	v_mfma_f32_16x16x32_bf16 v[72:75], v[152:155], v[176:179], v[72:75]
	v_mfma_f32_16x16x32_bf16 v[68:71], v[156:159], v[176:179], v[68:71]
	v_mfma_f32_16x16x32_bf16 v[64:67], v[160:163], v[176:179], v[64:67]
	global_load_lds_dwordx4 v[164:165], off
	s_waitcnt lgkmcnt(3)
	v_mfma_f32_16x16x32_bf16 v[60:63], v[148:151], v[180:183], v[60:63]
	v_mfma_f32_16x16x32_bf16 v[56:59], v[152:155], v[180:183], v[56:59]
	v_mfma_f32_16x16x32_bf16 v[52:55], v[156:159], v[180:183], v[52:55]
	v_mfma_f32_16x16x32_bf16 v[48:51], v[160:163], v[180:183], v[48:51]
	s_waitcnt lgkmcnt(2)
	v_mfma_f32_16x16x32_bf16 v[44:47], v[148:151], v[184:187], v[44:47]
	v_mfma_f32_16x16x32_bf16 v[40:43], v[152:155], v[184:187], v[40:43]
	v_mfma_f32_16x16x32_bf16 v[36:39], v[156:159], v[184:187], v[36:39]
	v_mfma_f32_16x16x32_bf16 v[28:31], v[160:163], v[184:187], v[28:31]
	s_waitcnt lgkmcnt(1)
	v_mfma_f32_16x16x32_bf16 v[24:27], v[148:151], v[188:191], v[24:27]
	v_mfma_f32_16x16x32_bf16 v[20:23], v[152:155], v[188:191], v[20:23]
	v_mfma_f32_16x16x32_bf16 v[16:19], v[156:159], v[188:191], v[16:19]
	v_mfma_f32_16x16x32_bf16 v[12:15], v[160:163], v[188:191], v[12:15]
	s_waitcnt vmcnt(0)
	s_barrier
	s_waitcnt lgkmcnt(0)
	v_mfma_f32_16x16x32_bf16 v[8:11], v[148:151], v[192:195], v[8:11]
	v_mfma_f32_16x16x32_bf16 v[4:7], v[152:155], v[192:195], v[4:7]
	v_mfma_f32_16x16x32_bf16 v[0:3], v[156:159], v[192:195], v[0:3]
	v_mfma_f32_16x16x32_bf16 v[32:35], v[160:163], v[192:195], v[32:35]
	s_cbranch_vccnz .LBB0_503
	v_lshrrev_b32_e32 v130, 2, v138
	s_lshl_b32 s2, s46, 8
	v_and_b32_e32 v130, 12, v130
	s_add_i32 s2, s2, s54
	v_lshl_or_b32 v130, s45, 8, v130
	v_and_or_b32 v128, v138, 15, s2
	v_or_b32_e32 v132, s82, v130
	v_lshlrev_b64 v[130:131], 13, v[128:129]
	v_ashrrev_i32_e32 v133, 31, v132
	v_lshl_add_u64 v[134:135], s[40:41], 0, v[130:131]
	v_lshlrev_b64 v[132:133], 2, v[132:133]
	v_lshl_add_u64 v[138:139], v[134:135], 0, v[132:133]
	global_load_dwordx4 v[134:137], v[138:139], off
	v_lshl_add_u64 v[140:141], s[70:71], 0, v[130:131]
	v_lshl_add_u64 v[140:141], v[140:141], 0, v[132:133]
	s_lshr_b32 s2, s33, 3
	s_add_i32 s44, s44, s84
	s_add_i32 s37, s37, s2
	s_cmp_gt_i32 s44, 31
	s_waitcnt vmcnt(0)
	v_pk_add_f32 v[126:127], v[126:127], v[136:137]
	v_pk_add_f32 v[124:125], v[124:125], v[134:135]
	global_store_dwordx4 v[140:141], v[124:127], off
	global_load_dwordx4 v[124:127], v[138:139], off offset:64
	s_waitcnt vmcnt(0)
	v_pk_add_f32 v[122:123], v[122:123], v[126:127]
	v_pk_add_f32 v[120:121], v[120:121], v[124:125]
	global_store_dwordx4 v[140:141], v[120:123], off offset:64
	global_load_dwordx4 v[120:123], v[138:139], off offset:128
	s_waitcnt vmcnt(0)
	v_pk_add_f32 v[118:119], v[118:119], v[122:123]
	v_pk_add_f32 v[116:117], v[116:117], v[120:121]
	global_store_dwordx4 v[140:141], v[116:119], off offset:128
	global_load_dwordx4 v[116:119], v[138:139], off offset:192
	v_or_b32_e32 v120, 0x20000, v130
	v_mov_b32_e32 v121, v131
	v_lshl_add_u64 v[122:123], s[40:41], 0, v[120:121]
	v_lshl_add_u64 v[122:123], v[122:123], 0, v[132:133]
	s_waitcnt vmcnt(0)
	v_pk_add_f32 v[114:115], v[114:115], v[118:119]
	v_pk_add_f32 v[112:113], v[112:113], v[116:117]
	global_store_dwordx4 v[140:141], v[112:115], off offset:192
	global_load_dwordx4 v[112:115], v[122:123], off
	v_lshl_add_u64 v[116:117], s[70:71], 0, v[120:121]
	v_lshl_add_u64 v[116:117], v[116:117], 0, v[132:133]
	s_waitcnt vmcnt(0)
	v_pk_add_f32 v[110:111], v[110:111], v[114:115]
	v_pk_add_f32 v[108:109], v[108:109], v[112:113]
	global_store_dwordx4 v[116:117], v[108:111], off
	global_load_dwordx4 v[108:111], v[122:123], off offset:64
	s_waitcnt vmcnt(0)
	v_pk_add_f32 v[106:107], v[106:107], v[110:111]
	v_pk_add_f32 v[104:105], v[104:105], v[108:109]
	global_store_dwordx4 v[116:117], v[104:107], off offset:64
	global_load_dwordx4 v[104:107], v[122:123], off offset:128
	s_waitcnt vmcnt(0)
	v_pk_add_f32 v[102:103], v[102:103], v[106:107]
	v_pk_add_f32 v[100:101], v[100:101], v[104:105]
	global_store_dwordx4 v[116:117], v[100:103], off offset:128
	global_load_dwordx4 v[100:103], v[122:123], off offset:192
	v_or_b32_e32 v104, 0x40000, v130
	v_mov_b32_e32 v105, v131
	v_lshl_add_u64 v[106:107], s[40:41], 0, v[104:105]
	v_lshl_add_u64 v[106:107], v[106:107], 0, v[132:133]
	s_waitcnt vmcnt(0)
; template <typename F> DI void for_tiles3(int MT, int NT, F f) {
;     const int b = blockIdx.x, G = gridDim.x, xcd = b & 7, slot = b >> 3, slots = G >> 3;
;     const int nsn = NT / 4, nsm = MT / 8;
;     for (int sidx = xcd; sidx < nsn * nsm; sidx += 8) {
;         const int sm = sidx / nsn, sn = sidx % nsn;
;         for (int tl = slot; tl < 32; tl += slots) f(sm * 8 + (tl & 7), sn * 4 + (tl >> 3));
;     }
; DI void phase4(const Params& p, unsigned char* smem) {
;     ...
; #pragma unroll
;         for (int i = 0; i < 8; ++i) {
;             const size_t m = (size_t)mt * 256 + wm * 128 + i * 16 + fr;
; #pragma unroll
;             for (int j = 0; j < 4; ++j) {
;                 const int c = nt * 256 + wn * 64 + j * 16 + fq * 4;
;                 const f32x4 xv = *(const f32x4*)(p.x + m * DM + c);
;                 *(f32x4*)(p.out + m * DM + c) = xv + acc[i][j];
;             }
;         }
	v_pk_add_f32 v[98:99], v[98:99], v[102:103]
	v_pk_add_f32 v[96:97], v[96:97], v[100:101]
	global_store_dwordx4 v[116:117], v[96:99], off offset:192
	global_load_dwordx4 v[96:99], v[106:107], off
	v_lshl_add_u64 v[100:101], s[70:71], 0, v[104:105]
	v_lshl_add_u64 v[100:101], v[100:101], 0, v[132:133]
	s_waitcnt vmcnt(0)
	v_pk_add_f32 v[94:95], v[94:95], v[98:99]
	v_pk_add_f32 v[92:93], v[92:93], v[96:97]
	global_store_dwordx4 v[100:101], v[92:95], off
	global_load_dwordx4 v[92:95], v[106:107], off offset:64
	s_waitcnt vmcnt(0)
	v_pk_add_f32 v[90:91], v[90:91], v[94:95]
	v_pk_add_f32 v[88:89], v[88:89], v[92:93]
	global_store_dwordx4 v[100:101], v[88:91], off offset:64
	global_load_dwordx4 v[88:91], v[106:107], off offset:128
	s_waitcnt vmcnt(0)
	v_pk_add_f32 v[86:87], v[86:87], v[90:91]
	v_pk_add_f32 v[84:85], v[84:85], v[88:89]
	global_store_dwordx4 v[100:101], v[84:87], off offset:128
	global_load_dwordx4 v[84:87], v[106:107], off offset:192
	v_or_b32_e32 v88, 0x60000, v130
	v_mov_b32_e32 v89, v131
	v_lshl_add_u64 v[90:91], s[40:41], 0, v[88:89]
	v_lshl_add_u64 v[90:91], v[90:91], 0, v[132:133]
	s_waitcnt vmcnt(0)
	v_pk_add_f32 v[82:83], v[82:83], v[86:87]
	v_pk_add_f32 v[80:81], v[80:81], v[84:85]
	global_store_dwordx4 v[100:101], v[80:83], off offset:192
	global_load_dwordx4 v[80:83], v[90:91], off
	v_lshl_add_u64 v[84:85], s[70:71], 0, v[88:89]
	v_lshl_add_u64 v[84:85], v[84:85], 0, v[132:133]
	s_waitcnt vmcnt(0)
	v_pk_add_f32 v[78:79], v[78:79], v[82:83]
	v_pk_add_f32 v[76:77], v[76:77], v[80:81]
	global_store_dwordx4 v[84:85], v[76:79], off
	global_load_dwordx4 v[76:79], v[90:91], off offset:64
	s_waitcnt vmcnt(0)
	v_pk_add_f32 v[74:75], v[74:75], v[78:79]
	v_pk_add_f32 v[72:73], v[72:73], v[76:77]
	global_store_dwordx4 v[84:85], v[72:75], off offset:64
	global_load_dwordx4 v[72:75], v[90:91], off offset:128
	s_waitcnt vmcnt(0)
	v_pk_add_f32 v[70:71], v[70:71], v[74:75]
	v_pk_add_f32 v[68:69], v[68:69], v[72:73]
	global_store_dwordx4 v[84:85], v[68:71], off offset:128
	global_load_dwordx4 v[68:71], v[90:91], off offset:192
	v_or_b32_e32 v72, 0x80000, v130
	v_mov_b32_e32 v73, v131
	v_lshl_add_u64 v[74:75], s[40:41], 0, v[72:73]
	v_lshl_add_u64 v[74:75], v[74:75], 0, v[132:133]
	s_waitcnt vmcnt(0)
	v_pk_add_f32 v[66:67], v[66:67], v[70:71]
	v_pk_add_f32 v[64:65], v[64:65], v[68:69]
	global_store_dwordx4 v[84:85], v[64:67], off offset:192
	global_load_dwordx4 v[64:67], v[74:75], off
	v_lshl_add_u64 v[68:69], s[70:71], 0, v[72:73]
	v_lshl_add_u64 v[68:69], v[68:69], 0, v[132:133]
	s_waitcnt vmcnt(0)
	v_pk_add_f32 v[62:63], v[62:63], v[66:67]
	v_pk_add_f32 v[60:61], v[60:61], v[64:65]
	global_store_dwordx4 v[68:69], v[60:63], off
	global_load_dwordx4 v[60:63], v[74:75], off offset:64
	s_waitcnt vmcnt(0)
	v_pk_add_f32 v[58:59], v[58:59], v[62:63]
	v_pk_add_f32 v[56:57], v[56:57], v[60:61]
	global_store_dwordx4 v[68:69], v[56:59], off offset:64
	global_load_dwordx4 v[56:59], v[74:75], off offset:128
	s_waitcnt vmcnt(0)
	v_pk_add_f32 v[54:55], v[54:55], v[58:59]
	v_pk_add_f32 v[52:53], v[52:53], v[56:57]
	global_store_dwordx4 v[68:69], v[52:55], off offset:128
	global_load_dwordx4 v[52:55], v[74:75], off offset:192
	v_or_b32_e32 v56, 0xa0000, v130
	v_mov_b32_e32 v57, v131
	v_lshl_add_u64 v[58:59], s[40:41], 0, v[56:57]
	v_lshl_add_u64 v[58:59], v[58:59], 0, v[132:133]
	s_waitcnt vmcnt(0)
	v_pk_add_f32 v[50:51], v[50:51], v[54:55]
	v_pk_add_f32 v[48:49], v[48:49], v[52:53]
	global_store_dwordx4 v[68:69], v[48:51], off offset:192
	global_load_dwordx4 v[48:51], v[58:59], off
	v_lshl_add_u64 v[52:53], s[70:71], 0, v[56:57]
	v_lshl_add_u64 v[52:53], v[52:53], 0, v[132:133]
	s_waitcnt vmcnt(0)
	v_pk_add_f32 v[46:47], v[46:47], v[50:51]
	v_pk_add_f32 v[44:45], v[44:45], v[48:49]
	global_store_dwordx4 v[52:53], v[44:47], off
	global_load_dwordx4 v[44:47], v[58:59], off offset:64
	s_waitcnt vmcnt(0)
	v_pk_add_f32 v[42:43], v[42:43], v[46:47]
	v_pk_add_f32 v[40:41], v[40:41], v[44:45]
	global_store_dwordx4 v[52:53], v[40:43], off offset:64
	global_load_dwordx4 v[40:43], v[58:59], off offset:128
	s_waitcnt vmcnt(0)
	v_pk_add_f32 v[38:39], v[38:39], v[42:43]
	v_pk_add_f32 v[36:37], v[36:37], v[40:41]
	global_store_dwordx4 v[52:53], v[36:39], off offset:128
	global_load_dwordx4 v[36:39], v[58:59], off offset:192
	v_or_b32_e32 v40, 0xc0000, v130
	v_mov_b32_e32 v41, v131
	v_lshl_add_u64 v[42:43], s[40:41], 0, v[40:41]
	v_lshl_add_u64 v[42:43], v[42:43], 0, v[132:133]
	v_or_b32_e32 v130, 0xe0000, v130
	s_waitcnt vmcnt(0)
	v_pk_add_f32 v[30:31], v[30:31], v[38:39]
	v_pk_add_f32 v[28:29], v[28:29], v[36:37]
	global_store_dwordx4 v[52:53], v[28:31], off offset:192
	global_load_dwordx4 v[28:31], v[42:43], off
	v_lshl_add_u64 v[36:37], s[70:71], 0, v[40:41]
	v_lshl_add_u64 v[36:37], v[36:37], 0, v[132:133]
	s_waitcnt vmcnt(0)
	v_pk_add_f32 v[26:27], v[26:27], v[30:31]
	v_pk_add_f32 v[24:25], v[24:25], v[28:29]
	global_store_dwordx4 v[36:37], v[24:27], off
	global_load_dwordx4 v[24:27], v[42:43], off offset:64
	s_waitcnt vmcnt(0)
	v_pk_add_f32 v[22:23], v[22:23], v[26:27]
	v_pk_add_f32 v[20:21], v[20:21], v[24:25]
	global_store_dwordx4 v[36:37], v[20:23], off offset:64
	global_load_dwordx4 v[20:23], v[42:43], off offset:128
	s_waitcnt vmcnt(0)
	v_pk_add_f32 v[18:19], v[18:19], v[22:23]
	v_pk_add_f32 v[16:17], v[16:17], v[20:21]
	global_store_dwordx4 v[36:37], v[16:19], off offset:128
	global_load_dwordx4 v[16:19], v[42:43], off offset:192
	v_lshl_add_u64 v[20:21], s[40:41], 0, v[130:131]
	v_lshl_add_u64 v[20:21], v[20:21], 0, v[132:133]
	s_waitcnt vmcnt(0)
	v_pk_add_f32 v[14:15], v[14:15], v[18:19]
	v_pk_add_f32 v[12:13], v[12:13], v[16:17]
	global_store_dwordx4 v[36:37], v[12:15], off offset:192
	global_load_dwordx4 v[12:15], v[20:21], off
	v_lshl_add_u64 v[16:17], s[70:71], 0, v[130:131]
	v_lshl_add_u64 v[16:17], v[16:17], 0, v[132:133]
	s_waitcnt vmcnt(0)
	v_pk_add_f32 v[10:11], v[10:11], v[14:15]
	v_pk_add_f32 v[8:9], v[8:9], v[12:13]
	global_store_dwordx4 v[16:17], v[8:11], off
	global_load_dwordx4 v[8:11], v[20:21], off offset:64
	s_waitcnt vmcnt(0)
	v_pk_add_f32 v[6:7], v[6:7], v[10:11]
	v_pk_add_f32 v[4:5], v[4:5], v[8:9]
	global_store_dwordx4 v[16:17], v[4:7], off offset:64
	global_load_dwordx4 v[4:7], v[20:21], off offset:128
	s_waitcnt vmcnt(0)
	v_pk_add_f32 v[2:3], v[2:3], v[6:7]
	v_pk_add_f32 v[0:1], v[0:1], v[4:5]
	global_store_dwordx4 v[16:17], v[0:3], off offset:128
	global_load_dwordx4 v[0:3], v[20:21], off offset:192
	s_waitcnt vmcnt(0)
	v_pk_add_f32 v[2:3], v[34:35], v[2:3]
	v_pk_add_f32 v[0:1], v[32:33], v[0:1]
	global_store_dwordx4 v[16:17], v[0:3], off offset:192
	s_cbranch_scc0 .LBB0_502
	s_branch .LBB0_499
